# static priority (lever 4): waves 4-7 at s_setprio 1 for the whole kernel, per-MFMA-block setprio flips removed from the six K-loops
# speedup vs baseline: 1.0034x; 1.0034x over previous
_Z8mega_fwd6Params:
	s_load_dwordx2 s[42:43], s[0:1], 0x118
	s_load_dword s72, s[0:1], 0x120
	s_add_u32 s4, s0, 0x118
	s_addc_u32 s5, s1, 0
	v_and_b32_e32 v218, 0x3ff, v0
	v_writelane_b32 v252, s4, 0
	v_readfirstlane_b32 s75, v218
	v_cmp_gt_u32_e32 vcc, 2, v218
	v_writelane_b32 v252, s5, 1
	s_and_saveexec_b64 s[4:5], vcc
	v_lshlrev_b32_e32 v1, 2, v218
	v_mov_b32_e32 v2, 0
	ds_write_b32 v1, v2
	s_or_b64 exec, exec, s[4:5]
	s_cmpk_lt_u32 s75, 0x100
	s_cbranch_scc1 .Lprio_lo
	s_setprio 1
.Lprio_lo:
	s_mov_b64 s[4:5], s[0:1]
	s_waitcnt lgkmcnt(0)
	s_barrier
	s_load_dwordx2 s[40:41], s[4:5], 0x110
	s_getreg_b32 s3, hwreg(HW_REG_XCC_ID, 0, 4)
	s_and_b32 s33, s3, 15
	v_cmp_eq_u32_e64 s[4:5], 0, v218
	s_and_saveexec_b64 s[6:7], s[4:5]
	s_cbranch_execz .LBB0_5
	s_mov_b64 s[8:9], exec
	v_mbcnt_lo_u32_b32 v1, s8, 0
	v_mbcnt_hi_u32_b32 v1, s9, v1
	v_cmp_eq_u32_e32 vcc, 0, v1
	s_and_b64 s[10:11], exec, vcc
	s_mov_b64 exec, s[10:11]
	s_cbranch_execz .LBB0_5
	s_lshl_b32 s3, s33, 8
	s_bcnt1_i32_b64 s8, s[8:9]
	v_mov_b32_e32 v1, s3
	v_mov_b32_e32 v2, s8
	s_waitcnt lgkmcnt(0)
	global_atomic_add v1, v2, s[40:41] offset:1024

.LBB0_251:
	ds_read_b128 v[154:157], v151
	ds_read_b128 v[158:161], v151 offset:1024
	ds_read_b128 v[162:165], v151 offset:2048
	ds_read_b128 v[166:169], v151 offset:3072
	ds_read_b128 v[170:173], v152
	ds_read_b128 v[174:177], v152 offset:1024
	ds_read_b128 v[178:181], v152 offset:2048
	ds_read_b128 v[186:189], v152 offset:3072
	s_add_u32 s38, s36, 0xfff80080
	s_addc_u32 s39, s37, -1
	s_cmp_eq_u32 s74, 28
	s_cselect_b32 s45, s25, s39
	s_cselect_b32 s44, s34, s38
	s_cselect_b32 s39, s23, s71
	s_cselect_b32 s38, s35, s70
	v_lshl_add_u64 v[182:183], s[36:37], 0, v[142:143]
	s_add_i32 m0, s31, 0xc000
	ds_read_b128 v[190:193], v153
	ds_read_b128 v[194:197], v153 offset:1024
	ds_read_b128 v[202:205], v153 offset:2048
	ds_read_b128 v[206:209], v153 offset:3072
	ds_read_b128 v[210:213], v153 offset:4096
	ds_read_b128 v[214:217], v153 offset:5120
	ds_read_b128 v[226:229], v153 offset:6144
	ds_read_b128 v[230:233], v153 offset:7168
	global_load_lds_dwordx4 v[182:183], off
	v_lshl_add_u64 v[182:183], s[36:37], 0, v[140:141]
	s_add_i32 m0, s31, 0xe000
	s_nop 0
	global_load_lds_dwordx4 v[182:183], off
	s_waitcnt vmcnt(8)
	s_waitcnt lgkmcnt(0)
	s_barrier
	s_waitcnt lgkmcnt(0)
	v_mfma_f32_16x16x32_bf16 v[126:129], v[154:157], v[190:193], v[126:129]
	v_mfma_f32_16x16x32_bf16 v[126:129], v[158:161], v[194:197], v[126:129]
	v_mfma_f32_16x16x32_bf16 v[122:125], v[162:165], v[190:193], v[122:125]
	v_mfma_f32_16x16x32_bf16 v[122:125], v[166:169], v[194:197], v[122:125]
	v_mfma_f32_16x16x32_bf16 v[118:121], v[170:173], v[190:193], v[118:121]
	v_mfma_f32_16x16x32_bf16 v[118:121], v[174:177], v[194:197], v[118:121]
	v_mfma_f32_16x16x32_bf16 v[114:117], v[178:181], v[190:193], v[114:117]
	v_mfma_f32_16x16x32_bf16 v[114:117], v[186:189], v[194:197], v[114:117]
	v_mfma_f32_16x16x32_bf16 v[110:113], v[154:157], v[202:205], v[110:113]
	v_mfma_f32_16x16x32_bf16 v[110:113], v[158:161], v[206:209], v[110:113]
	v_mfma_f32_16x16x32_bf16 v[106:109], v[162:165], v[202:205], v[106:109]
	v_mfma_f32_16x16x32_bf16 v[106:109], v[166:169], v[206:209], v[106:109]
	v_mfma_f32_16x16x32_bf16 v[102:105], v[170:173], v[202:205], v[102:105]
	v_mfma_f32_16x16x32_bf16 v[102:105], v[174:177], v[206:209], v[102:105]
	v_mfma_f32_16x16x32_bf16 v[98:101], v[178:181], v[202:205], v[98:101]
	v_mfma_f32_16x16x32_bf16 v[98:101], v[186:189], v[206:209], v[98:101]
	v_mfma_f32_16x16x32_bf16 v[94:97], v[154:157], v[210:213], v[94:97]
	v_mfma_f32_16x16x32_bf16 v[94:97], v[158:161], v[214:217], v[94:97]
	v_mfma_f32_16x16x32_bf16 v[90:93], v[162:165], v[210:213], v[90:93]
	v_mfma_f32_16x16x32_bf16 v[90:93], v[166:169], v[214:217], v[90:93]
	v_mfma_f32_16x16x32_bf16 v[86:89], v[170:173], v[210:213], v[86:89]
	v_mfma_f32_16x16x32_bf16 v[86:89], v[174:177], v[214:217], v[86:89]
	v_mfma_f32_16x16x32_bf16 v[82:85], v[178:181], v[210:213], v[82:85]
	v_mfma_f32_16x16x32_bf16 v[82:85], v[186:189], v[214:217], v[82:85]
	v_mfma_f32_16x16x32_bf16 v[78:81], v[154:157], v[226:229], v[78:81]
	v_mfma_f32_16x16x32_bf16 v[78:81], v[158:161], v[230:233], v[78:81]
	v_mfma_f32_16x16x32_bf16 v[74:77], v[162:165], v[226:229], v[74:77]
	v_mfma_f32_16x16x32_bf16 v[74:77], v[166:169], v[230:233], v[74:77]
	v_mfma_f32_16x16x32_bf16 v[70:73], v[170:173], v[226:229], v[70:73]
	v_mfma_f32_16x16x32_bf16 v[70:73], v[174:177], v[230:233], v[70:73]
	v_mfma_f32_16x16x32_bf16 v[66:69], v[178:181], v[226:229], v[66:69]
	v_mfma_f32_16x16x32_bf16 v[66:69], v[186:189], v[230:233], v[66:69]
	s_barrier
	s_add_i32 s76, s66, s53
	v_lshl_add_u64 v[182:183], s[38:39], 0, v[134:135]
	s_mov_b32 m0, s76
	ds_read_b128 v[190:193], v153 offset:16384
	ds_read_b128 v[194:197], v153 offset:17408
	ds_read_b128 v[202:205], v153 offset:18432
	ds_read_b128 v[206:209], v153 offset:19456
	ds_read_b128 v[210:213], v153 offset:20480
	ds_read_b128 v[214:217], v153 offset:21504
	ds_read_b128 v[226:229], v153 offset:22528
	ds_read_b128 v[230:233], v153 offset:23552
	global_load_lds_dwordx4 v[182:183], off
	s_add_i32 m0, s76, 0x2000
	s_add_u32 s76, s38, 0x80000
	v_lshl_add_u64 v[234:235], s[38:39], 0, v[130:131]
	s_addc_u32 s77, s39, 0
	s_add_i32 s78, s67, s53
	global_load_lds_dwordx4 v[234:235], off
	v_lshl_add_u64 v[236:237], s[76:77], 0, v[134:135]
	s_mov_b32 m0, s78
	v_lshl_add_u64 v[238:239], s[44:45], 0, v[132:133]
	global_load_lds_dwordx4 v[236:237], off
	v_lshl_add_u64 v[236:237], s[76:77], 0, v[130:131]
	s_add_i32 m0, s78, 0x2000
	s_nop 0
	global_load_lds_dwordx4 v[236:237], off
	v_lshl_add_u64 v[236:237], s[44:45], 0, v[136:137]
	s_mov_b32 m0, s31
	s_nop 0
	global_load_lds_dwordx4 v[236:237], off
	s_mov_b32 m0, s56
	s_nop 0
	global_load_lds_dwordx4 v[238:239], off
	s_waitcnt vmcnt(8)
	s_waitcnt lgkmcnt(0)
	s_barrier
	s_waitcnt lgkmcnt(0)
	v_mfma_f32_16x16x32_bf16 v[62:65], v[154:157], v[190:193], v[62:65]
	v_mfma_f32_16x16x32_bf16 v[62:65], v[158:161], v[194:197], v[62:65]
	v_mfma_f32_16x16x32_bf16 v[58:61], v[162:165], v[190:193], v[58:61]
	v_mfma_f32_16x16x32_bf16 v[58:61], v[166:169], v[194:197], v[58:61]
	v_mfma_f32_16x16x32_bf16 v[54:57], v[170:173], v[190:193], v[54:57]
	v_mfma_f32_16x16x32_bf16 v[54:57], v[174:177], v[194:197], v[54:57]
	v_mfma_f32_16x16x32_bf16 v[50:53], v[178:181], v[190:193], v[50:53]
	v_mfma_f32_16x16x32_bf16 v[50:53], v[186:189], v[194:197], v[50:53]
	v_mfma_f32_16x16x32_bf16 v[46:49], v[154:157], v[202:205], v[46:49]
	v_mfma_f32_16x16x32_bf16 v[46:49], v[158:161], v[206:209], v[46:49]
	v_mfma_f32_16x16x32_bf16 v[42:45], v[162:165], v[202:205], v[42:45]
	v_mfma_f32_16x16x32_bf16 v[42:45], v[166:169], v[206:209], v[42:45]
	v_mfma_f32_16x16x32_bf16 v[38:41], v[170:173], v[202:205], v[38:41]
	v_mfma_f32_16x16x32_bf16 v[38:41], v[174:177], v[206:209], v[38:41]
	v_mfma_f32_16x16x32_bf16 v[34:37], v[178:181], v[202:205], v[34:37]
	v_mfma_f32_16x16x32_bf16 v[34:37], v[186:189], v[206:209], v[34:37]
	v_mfma_f32_16x16x32_bf16 v[30:33], v[154:157], v[210:213], v[30:33]
	v_mfma_f32_16x16x32_bf16 v[30:33], v[158:161], v[214:217], v[30:33]
	v_mfma_f32_16x16x32_bf16 v[26:29], v[162:165], v[210:213], v[26:29]
	v_mfma_f32_16x16x32_bf16 v[26:29], v[166:169], v[214:217], v[26:29]
	v_mfma_f32_16x16x32_bf16 v[22:25], v[170:173], v[210:213], v[22:25]
	v_mfma_f32_16x16x32_bf16 v[22:25], v[174:177], v[214:217], v[22:25]
	v_mfma_f32_16x16x32_bf16 v[18:21], v[178:181], v[210:213], v[18:21]
	v_mfma_f32_16x16x32_bf16 v[18:21], v[186:189], v[214:217], v[18:21]
	v_mfma_f32_16x16x32_bf16 v[14:17], v[154:157], v[226:229], v[14:17]
	v_mfma_f32_16x16x32_bf16 v[14:17], v[158:161], v[230:233], v[14:17]
	v_mfma_f32_16x16x32_bf16 v[10:13], v[162:165], v[226:229], v[10:13]
	v_mfma_f32_16x16x32_bf16 v[10:13], v[166:169], v[230:233], v[10:13]
	v_mfma_f32_16x16x32_bf16 v[6:9], v[170:173], v[226:229], v[6:9]
	v_mfma_f32_16x16x32_bf16 v[6:9], v[174:177], v[230:233], v[6:9]
	v_mfma_f32_16x16x32_bf16 v[2:5], v[178:181], v[226:229], v[2:5]
	v_mfma_f32_16x16x32_bf16 v[2:5], v[186:189], v[230:233], v[2:5]
	s_barrier
	s_add_i32 s76, 16, 0x18000
	v_add_u32_e32 v138, s76, v150
	s_add_i32 s77, 16, 0x1c000
	ds_read_b128 v[154:157], v138
	ds_read_b128 v[158:161], v138 offset:1024
	ds_read_b128 v[162:165], v138 offset:2048
	ds_read_b128 v[166:169], v138 offset:3072
	v_add_u32_e32 v138, s77, v150
	ds_read_b128 v[170:173], v138
	ds_read_b128 v[174:177], v138 offset:1024
	ds_read_b128 v[178:181], v138 offset:2048
	ds_read_b128 v[186:189], v138 offset:3072
	s_add_u32 s44, s44, 0x80000
	s_addc_u32 s45, s45, 0
	s_mov_b32 m0, s57
	v_lshl_add_u64 v[240:241], s[44:45], 0, v[136:137]
	ds_read_b128 v[190:193], v153 offset:32768
	ds_read_b128 v[194:197], v153 offset:33792
	ds_read_b128 v[202:205], v153 offset:34816
	ds_read_b128 v[206:209], v153 offset:35840
	ds_read_b128 v[210:213], v153 offset:36864
	ds_read_b128 v[214:217], v153 offset:37888
	ds_read_b128 v[226:229], v153 offset:38912
	ds_read_b128 v[230:233], v153 offset:39936
	global_load_lds_dwordx4 v[240:241], off
	v_lshl_add_u64 v[240:241], s[44:45], 0, v[132:133]
	s_mov_b32 m0, s58
	s_nop 0
	global_load_lds_dwordx4 v[240:241], off
	s_waitcnt vmcnt(8)
	s_waitcnt lgkmcnt(0)
	s_barrier
	s_waitcnt lgkmcnt(0)
	v_mfma_f32_16x16x32_bf16 v[126:129], v[154:157], v[190:193], v[126:129]
	v_mfma_f32_16x16x32_bf16 v[126:129], v[158:161], v[194:197], v[126:129]
	v_mfma_f32_16x16x32_bf16 v[122:125], v[162:165], v[190:193], v[122:125]
	v_mfma_f32_16x16x32_bf16 v[122:125], v[166:169], v[194:197], v[122:125]
	v_mfma_f32_16x16x32_bf16 v[118:121], v[170:173], v[190:193], v[118:121]
	v_mfma_f32_16x16x32_bf16 v[118:121], v[174:177], v[194:197], v[118:121]
	v_mfma_f32_16x16x32_bf16 v[114:117], v[178:181], v[190:193], v[114:117]
	v_mfma_f32_16x16x32_bf16 v[114:117], v[186:189], v[194:197], v[114:117]
	v_mfma_f32_16x16x32_bf16 v[110:113], v[154:157], v[202:205], v[110:113]
	v_mfma_f32_16x16x32_bf16 v[110:113], v[158:161], v[206:209], v[110:113]
	v_mfma_f32_16x16x32_bf16 v[106:109], v[162:165], v[202:205], v[106:109]
	v_mfma_f32_16x16x32_bf16 v[106:109], v[166:169], v[206:209], v[106:109]
	v_mfma_f32_16x16x32_bf16 v[102:105], v[170:173], v[202:205], v[102:105]
	v_mfma_f32_16x16x32_bf16 v[102:105], v[174:177], v[206:209], v[102:105]
	v_mfma_f32_16x16x32_bf16 v[98:101], v[178:181], v[202:205], v[98:101]
	v_mfma_f32_16x16x32_bf16 v[98:101], v[186:189], v[206:209], v[98:101]
	v_mfma_f32_16x16x32_bf16 v[94:97], v[154:157], v[210:213], v[94:97]
	v_mfma_f32_16x16x32_bf16 v[94:97], v[158:161], v[214:217], v[94:97]
	v_mfma_f32_16x16x32_bf16 v[90:93], v[162:165], v[210:213], v[90:93]
	v_mfma_f32_16x16x32_bf16 v[90:93], v[166:169], v[214:217], v[90:93]
	v_mfma_f32_16x16x32_bf16 v[86:89], v[170:173], v[210:213], v[86:89]
	v_mfma_f32_16x16x32_bf16 v[86:89], v[174:177], v[214:217], v[86:89]
	v_mfma_f32_16x16x32_bf16 v[82:85], v[178:181], v[210:213], v[82:85]
	v_mfma_f32_16x16x32_bf16 v[82:85], v[186:189], v[214:217], v[82:85]
	v_mfma_f32_16x16x32_bf16 v[78:81], v[154:157], v[226:229], v[78:81]
	v_mfma_f32_16x16x32_bf16 v[78:81], v[158:161], v[230:233], v[78:81]
	v_mfma_f32_16x16x32_bf16 v[74:77], v[162:165], v[226:229], v[74:77]
	v_mfma_f32_16x16x32_bf16 v[74:77], v[166:169], v[230:233], v[74:77]
	v_mfma_f32_16x16x32_bf16 v[70:73], v[170:173], v[226:229], v[70:73]
	v_mfma_f32_16x16x32_bf16 v[70:73], v[174:177], v[230:233], v[70:73]
	v_mfma_f32_16x16x32_bf16 v[66:69], v[178:181], v[226:229], v[66:69]
	v_mfma_f32_16x16x32_bf16 v[66:69], v[186:189], v[230:233], v[66:69]
	s_barrier
	s_add_i32 s44, s76, s53
	v_lshl_add_u64 v[182:183], v[182:183], 0, s[18:19]
	s_mov_b32 m0, s44
	ds_read_b128 v[190:193], v153 offset:49152
	ds_read_b128 v[194:197], v153 offset:50176
	ds_read_b128 v[202:205], v153 offset:51200
	ds_read_b128 v[206:209], v153 offset:52224
	ds_read_b128 v[210:213], v153 offset:53248
	ds_read_b128 v[214:217], v153 offset:54272
	ds_read_b128 v[226:229], v153 offset:55296
	ds_read_b128 v[230:233], v153 offset:56320
	global_load_lds_dwordx4 v[182:183], off
	s_add_i32 m0, s44, 0x2000
	s_add_u32 s38, s38, 0x80080
	v_lshl_add_u64 v[182:183], v[234:235], 0, s[18:19]
	s_addc_u32 s39, s39, 0
	s_add_i32 s44, s77, s53
	global_load_lds_dwordx4 v[182:183], off
	v_lshl_add_u64 v[182:183], s[38:39], 0, v[134:135]
	s_mov_b32 m0, s44
	s_nop 0
	global_load_lds_dwordx4 v[182:183], off
	v_lshl_add_u64 v[182:183], s[38:39], 0, v[130:131]
	s_add_i32 m0, s44, 0x2000
	s_nop 0
	global_load_lds_dwordx4 v[182:183], off
	v_lshl_add_u64 v[182:183], v[236:237], 0, s[18:19]
	s_mov_b32 m0, s62
	s_nop 0
	global_load_lds_dwordx4 v[182:183], off
	v_lshl_add_u64 v[182:183], v[238:239], 0, s[18:19]
	s_mov_b32 m0, s63
	s_nop 0
	global_load_lds_dwordx4 v[182:183], off
	s_waitcnt vmcnt(8)
	s_waitcnt lgkmcnt(0)
	s_barrier
	s_waitcnt lgkmcnt(0)
	v_mfma_f32_16x16x32_bf16 v[62:65], v[154:157], v[190:193], v[62:65]
	v_mfma_f32_16x16x32_bf16 v[62:65], v[158:161], v[194:197], v[62:65]
	v_mfma_f32_16x16x32_bf16 v[58:61], v[162:165], v[190:193], v[58:61]
	v_mfma_f32_16x16x32_bf16 v[58:61], v[166:169], v[194:197], v[58:61]
	v_mfma_f32_16x16x32_bf16 v[54:57], v[170:173], v[190:193], v[54:57]
	v_mfma_f32_16x16x32_bf16 v[54:57], v[174:177], v[194:197], v[54:57]
	v_mfma_f32_16x16x32_bf16 v[50:53], v[178:181], v[190:193], v[50:53]
	v_mfma_f32_16x16x32_bf16 v[50:53], v[186:189], v[194:197], v[50:53]
	v_mfma_f32_16x16x32_bf16 v[46:49], v[154:157], v[202:205], v[46:49]
	v_mfma_f32_16x16x32_bf16 v[46:49], v[158:161], v[206:209], v[46:49]
	v_mfma_f32_16x16x32_bf16 v[42:45], v[162:165], v[202:205], v[42:45]
	v_mfma_f32_16x16x32_bf16 v[42:45], v[166:169], v[206:209], v[42:45]
	v_mfma_f32_16x16x32_bf16 v[38:41], v[170:173], v[202:205], v[38:41]
	v_mfma_f32_16x16x32_bf16 v[38:41], v[174:177], v[206:209], v[38:41]
	v_mfma_f32_16x16x32_bf16 v[34:37], v[178:181], v[202:205], v[34:37]
	v_mfma_f32_16x16x32_bf16 v[34:37], v[186:189], v[206:209], v[34:37]
	v_mfma_f32_16x16x32_bf16 v[30:33], v[154:157], v[210:213], v[30:33]
	v_mfma_f32_16x16x32_bf16 v[30:33], v[158:161], v[214:217], v[30:33]
	v_mfma_f32_16x16x32_bf16 v[26:29], v[162:165], v[210:213], v[26:29]
	v_mfma_f32_16x16x32_bf16 v[26:29], v[166:169], v[214:217], v[26:29]
	v_mfma_f32_16x16x32_bf16 v[22:25], v[170:173], v[210:213], v[22:25]
	v_mfma_f32_16x16x32_bf16 v[22:25], v[174:177], v[214:217], v[22:25]
	v_mfma_f32_16x16x32_bf16 v[18:21], v[178:181], v[210:213], v[18:21]
	v_mfma_f32_16x16x32_bf16 v[18:21], v[186:189], v[214:217], v[18:21]
	v_mfma_f32_16x16x32_bf16 v[14:17], v[154:157], v[226:229], v[14:17]
	v_mfma_f32_16x16x32_bf16 v[14:17], v[158:161], v[230:233], v[14:17]
	v_mfma_f32_16x16x32_bf16 v[10:13], v[162:165], v[226:229], v[10:13]
	v_mfma_f32_16x16x32_bf16 v[10:13], v[166:169], v[230:233], v[10:13]
	v_mfma_f32_16x16x32_bf16 v[6:9], v[170:173], v[226:229], v[6:9]
	v_mfma_f32_16x16x32_bf16 v[6:9], v[174:177], v[230:233], v[6:9]
	v_mfma_f32_16x16x32_bf16 v[2:5], v[178:181], v[226:229], v[2:5]
	v_mfma_f32_16x16x32_bf16 v[2:5], v[186:189], v[230:233], v[2:5]
	s_barrier
	s_add_i32 s74, s74, 2
	s_add_u32 s70, s70, 0x100
	s_addc_u32 s71, s71, 0
	s_add_u32 s36, s36, 0x100
	s_addc_u32 s37, s37, 0
	s_cmp_gt_u32 s74, 29
	s_cbranch_scc0 .LBB0_251
	s_and_b64 vcc, exec, s[20:21]
	s_cbranch_vccz .LBB0_254
	s_barrier

.LBB0_335:
	ds_read_b128 v[130:133], v165
	ds_read_b128 v[134:137], v165 offset:1024
	ds_read_b128 v[138:141], v165 offset:2048
	ds_read_b128 v[142:145], v165 offset:3072
	ds_read_b128 v[168:171], v166
	ds_read_b128 v[172:175], v166 offset:1024
	ds_read_b128 v[176:179], v166 offset:2048
	ds_read_b128 v[180:183], v166 offset:3072
	s_add_u32 s64, s62, 0x100
	s_addc_u32 s65, s63, 0
	s_cmpk_eq_i32 s95, 0x52
	s_cselect_b32 s69, s9, s65
	s_cselect_b32 s68, s8, s64
	s_cselect_b32 s67, s61, s35
	s_cselect_b32 s66, s60, s34
	v_lshl_add_u64 v[160:161], s[62:63], 0, v[154:155]
	s_add_i32 m0, s78, 0xc000
	ds_read_b128 v[186:189], v167
	ds_read_b128 v[190:193], v167 offset:1024
	ds_read_b128 v[194:197], v167 offset:2048
	ds_read_b128 v[202:205], v167 offset:3072
	ds_read_b128 v[206:209], v167 offset:4096
	ds_read_b128 v[210:213], v167 offset:5120
	ds_read_b128 v[214:217], v167 offset:6144
	ds_read_b128 v[226:229], v167 offset:7168
	global_load_lds_dwordx4 v[160:161], off
	v_lshl_add_u64 v[160:161], s[62:63], 0, v[152:153]
	s_add_i32 m0, s78, 0xe000
	s_nop 0
	global_load_lds_dwordx4 v[160:161], off
	s_waitcnt vmcnt(8)
	s_waitcnt lgkmcnt(0)
	s_barrier
	s_waitcnt lgkmcnt(0)
	v_mfma_f32_16x16x32_bf16 v[126:129], v[130:133], v[186:189], v[126:129]
	v_mfma_f32_16x16x32_bf16 v[126:129], v[134:137], v[190:193], v[126:129]
	v_mfma_f32_16x16x32_bf16 v[122:125], v[138:141], v[186:189], v[122:125]
	v_mfma_f32_16x16x32_bf16 v[122:125], v[142:145], v[190:193], v[122:125]
	v_mfma_f32_16x16x32_bf16 v[106:109], v[168:171], v[186:189], v[106:109]
	v_mfma_f32_16x16x32_bf16 v[106:109], v[172:175], v[190:193], v[106:109]
	v_mfma_f32_16x16x32_bf16 v[98:101], v[176:179], v[186:189], v[98:101]
	v_mfma_f32_16x16x32_bf16 v[98:101], v[180:183], v[190:193], v[98:101]
	v_mfma_f32_16x16x32_bf16 v[118:121], v[130:133], v[194:197], v[118:121]
	v_mfma_f32_16x16x32_bf16 v[118:121], v[134:137], v[202:205], v[118:121]
	v_mfma_f32_16x16x32_bf16 v[114:117], v[138:141], v[194:197], v[114:117]
	v_mfma_f32_16x16x32_bf16 v[114:117], v[142:145], v[202:205], v[114:117]
	v_mfma_f32_16x16x32_bf16 v[90:93], v[168:171], v[194:197], v[90:93]
	v_mfma_f32_16x16x32_bf16 v[90:93], v[172:175], v[202:205], v[90:93]
	v_mfma_f32_16x16x32_bf16 v[86:89], v[176:179], v[194:197], v[86:89]
	v_mfma_f32_16x16x32_bf16 v[86:89], v[180:183], v[202:205], v[86:89]
	v_mfma_f32_16x16x32_bf16 v[110:113], v[130:133], v[206:209], v[110:113]
	v_mfma_f32_16x16x32_bf16 v[110:113], v[134:137], v[210:213], v[110:113]
	v_mfma_f32_16x16x32_bf16 v[102:105], v[138:141], v[206:209], v[102:105]
	v_mfma_f32_16x16x32_bf16 v[102:105], v[142:145], v[210:213], v[102:105]
	v_mfma_f32_16x16x32_bf16 v[82:85], v[168:171], v[206:209], v[82:85]
	v_mfma_f32_16x16x32_bf16 v[82:85], v[172:175], v[210:213], v[82:85]
	v_mfma_f32_16x16x32_bf16 v[78:81], v[176:179], v[206:209], v[78:81]
	v_mfma_f32_16x16x32_bf16 v[78:81], v[180:183], v[210:213], v[78:81]
	v_mfma_f32_16x16x32_bf16 v[94:97], v[130:133], v[214:217], v[94:97]
	v_mfma_f32_16x16x32_bf16 v[94:97], v[134:137], v[226:229], v[94:97]
	v_mfma_f32_16x16x32_bf16 v[74:77], v[138:141], v[214:217], v[74:77]
	v_mfma_f32_16x16x32_bf16 v[74:77], v[142:145], v[226:229], v[74:77]
	v_mfma_f32_16x16x32_bf16 v[70:73], v[168:171], v[214:217], v[70:73]
	v_mfma_f32_16x16x32_bf16 v[70:73], v[172:175], v[226:229], v[70:73]
	v_mfma_f32_16x16x32_bf16 v[66:69], v[176:179], v[214:217], v[66:69]
	v_mfma_f32_16x16x32_bf16 v[66:69], v[180:183], v[226:229], v[66:69]
	s_barrier
	s_add_i32 s52, s89, s70
	v_lshl_add_u64 v[160:161], s[66:67], 0, v[148:149]
	s_mov_b32 m0, s52
	ds_read_b128 v[186:189], v167 offset:16384
	ds_read_b128 v[190:193], v167 offset:17408
	ds_read_b128 v[194:197], v167 offset:18432
	ds_read_b128 v[202:205], v167 offset:19456
	ds_read_b128 v[206:209], v167 offset:20480
	ds_read_b128 v[210:213], v167 offset:21504
	ds_read_b128 v[214:217], v167 offset:22528
	ds_read_b128 v[226:229], v167 offset:23552
	global_load_lds_dwordx4 v[160:161], off
	s_add_i32 m0, s52, 0x2000
	s_add_u32 s62, s66, 0x158000
	v_lshl_add_u64 v[230:231], s[66:67], 0, v[146:147]
	s_addc_u32 s63, s67, 0
	s_add_i32 s52, s90, s70
	global_load_lds_dwordx4 v[230:231], off
	v_lshl_add_u64 v[232:233], s[62:63], 0, v[148:149]
	s_mov_b32 m0, s52
	v_lshl_add_u64 v[234:235], s[68:69], 0, v[146:147]
	global_load_lds_dwordx4 v[232:233], off
	v_lshl_add_u64 v[232:233], s[62:63], 0, v[146:147]
	s_add_i32 m0, s52, 0x2000
	s_nop 0
	global_load_lds_dwordx4 v[232:233], off
	v_lshl_add_u64 v[232:233], s[68:69], 0, v[148:149]
	s_mov_b32 m0, s78
	s_nop 0
	global_load_lds_dwordx4 v[232:233], off
	s_mov_b32 m0, s79
	s_nop 0
	global_load_lds_dwordx4 v[234:235], off
	s_waitcnt vmcnt(8)
	s_waitcnt lgkmcnt(0)
	s_barrier
	s_waitcnt lgkmcnt(0)
	v_mfma_f32_16x16x32_bf16 v[62:65], v[130:133], v[186:189], v[62:65]
	v_mfma_f32_16x16x32_bf16 v[62:65], v[134:137], v[190:193], v[62:65]
	v_mfma_f32_16x16x32_bf16 v[58:61], v[138:141], v[186:189], v[58:61]
	v_mfma_f32_16x16x32_bf16 v[58:61], v[142:145], v[190:193], v[58:61]
	v_mfma_f32_16x16x32_bf16 v[42:45], v[168:171], v[186:189], v[42:45]
	v_mfma_f32_16x16x32_bf16 v[42:45], v[172:175], v[190:193], v[42:45]
	v_mfma_f32_16x16x32_bf16 v[34:37], v[176:179], v[186:189], v[34:37]
	v_mfma_f32_16x16x32_bf16 v[34:37], v[180:183], v[190:193], v[34:37]
	v_mfma_f32_16x16x32_bf16 v[54:57], v[130:133], v[194:197], v[54:57]
	v_mfma_f32_16x16x32_bf16 v[54:57], v[134:137], v[202:205], v[54:57]
	v_mfma_f32_16x16x32_bf16 v[50:53], v[138:141], v[194:197], v[50:53]
	v_mfma_f32_16x16x32_bf16 v[50:53], v[142:145], v[202:205], v[50:53]
	v_mfma_f32_16x16x32_bf16 v[26:29], v[168:171], v[194:197], v[26:29]
	v_mfma_f32_16x16x32_bf16 v[26:29], v[172:175], v[202:205], v[26:29]
	v_mfma_f32_16x16x32_bf16 v[22:25], v[176:179], v[194:197], v[22:25]
	v_mfma_f32_16x16x32_bf16 v[22:25], v[180:183], v[202:205], v[22:25]
	v_mfma_f32_16x16x32_bf16 v[46:49], v[130:133], v[206:209], v[46:49]
	v_mfma_f32_16x16x32_bf16 v[46:49], v[134:137], v[210:213], v[46:49]
	v_mfma_f32_16x16x32_bf16 v[38:41], v[138:141], v[206:209], v[38:41]
	v_mfma_f32_16x16x32_bf16 v[38:41], v[142:145], v[210:213], v[38:41]
	v_mfma_f32_16x16x32_bf16 v[18:21], v[168:171], v[206:209], v[18:21]
	v_mfma_f32_16x16x32_bf16 v[18:21], v[172:175], v[210:213], v[18:21]
	v_mfma_f32_16x16x32_bf16 v[14:17], v[176:179], v[206:209], v[14:17]
	v_mfma_f32_16x16x32_bf16 v[14:17], v[180:183], v[210:213], v[14:17]
	v_mfma_f32_16x16x32_bf16 v[30:33], v[130:133], v[214:217], v[30:33]
	v_mfma_f32_16x16x32_bf16 v[30:33], v[134:137], v[226:229], v[30:33]
	v_mfma_f32_16x16x32_bf16 v[10:13], v[138:141], v[214:217], v[10:13]
	v_mfma_f32_16x16x32_bf16 v[10:13], v[142:145], v[226:229], v[10:13]
	v_mfma_f32_16x16x32_bf16 v[6:9], v[168:171], v[214:217], v[6:9]
	v_mfma_f32_16x16x32_bf16 v[6:9], v[172:175], v[226:229], v[6:9]
	v_mfma_f32_16x16x32_bf16 v[2:5], v[176:179], v[214:217], v[2:5]
	v_mfma_f32_16x16x32_bf16 v[2:5], v[180:183], v[226:229], v[2:5]
	s_barrier
	s_add_i32 s52, 16, 0x18000
	s_add_i32 s53, 16, 0x1c000
	v_add_u32_e32 v142, s52, v164
	v_add_u32_e32 v150, s53, v164
	ds_read_b128 v[130:133], v142
	ds_read_b128 v[134:137], v142 offset:1024
	ds_read_b128 v[138:141], v142 offset:2048
	ds_read_b128 v[142:145], v142 offset:3072
	ds_read_b128 v[168:171], v150
	ds_read_b128 v[172:175], v150 offset:1024
	ds_read_b128 v[176:179], v150 offset:2048
	ds_read_b128 v[180:183], v150 offset:3072
	s_add_u32 s62, s68, 0x158000
	s_addc_u32 s63, s69, 0
	s_mov_b32 m0, s80
	v_lshl_add_u64 v[236:237], s[62:63], 0, v[148:149]
	ds_read_b128 v[186:189], v167 offset:32768
	ds_read_b128 v[190:193], v167 offset:33792
	ds_read_b128 v[194:197], v167 offset:34816
	ds_read_b128 v[202:205], v167 offset:35840
	ds_read_b128 v[206:209], v167 offset:36864
	ds_read_b128 v[210:213], v167 offset:37888
	ds_read_b128 v[214:217], v167 offset:38912
	ds_read_b128 v[226:229], v167 offset:39936
	global_load_lds_dwordx4 v[236:237], off
	v_lshl_add_u64 v[236:237], s[62:63], 0, v[146:147]
	s_mov_b32 m0, s81
	s_nop 0
	global_load_lds_dwordx4 v[236:237], off
	s_waitcnt vmcnt(8)
	s_waitcnt lgkmcnt(0)
	s_barrier
	s_waitcnt lgkmcnt(0)
	v_mfma_f32_16x16x32_bf16 v[126:129], v[130:133], v[186:189], v[126:129]
	v_mfma_f32_16x16x32_bf16 v[126:129], v[134:137], v[190:193], v[126:129]
	v_mfma_f32_16x16x32_bf16 v[122:125], v[138:141], v[186:189], v[122:125]
	v_mfma_f32_16x16x32_bf16 v[122:125], v[142:145], v[190:193], v[122:125]
	v_mfma_f32_16x16x32_bf16 v[106:109], v[168:171], v[186:189], v[106:109]
	v_mfma_f32_16x16x32_bf16 v[106:109], v[172:175], v[190:193], v[106:109]
	v_mfma_f32_16x16x32_bf16 v[98:101], v[176:179], v[186:189], v[98:101]
	v_mfma_f32_16x16x32_bf16 v[98:101], v[180:183], v[190:193], v[98:101]
	v_mfma_f32_16x16x32_bf16 v[118:121], v[130:133], v[194:197], v[118:121]
	v_mfma_f32_16x16x32_bf16 v[118:121], v[134:137], v[202:205], v[118:121]
	v_mfma_f32_16x16x32_bf16 v[114:117], v[138:141], v[194:197], v[114:117]
	v_mfma_f32_16x16x32_bf16 v[114:117], v[142:145], v[202:205], v[114:117]
	v_mfma_f32_16x16x32_bf16 v[90:93], v[168:171], v[194:197], v[90:93]
	v_mfma_f32_16x16x32_bf16 v[90:93], v[172:175], v[202:205], v[90:93]
	v_mfma_f32_16x16x32_bf16 v[86:89], v[176:179], v[194:197], v[86:89]
	v_mfma_f32_16x16x32_bf16 v[86:89], v[180:183], v[202:205], v[86:89]
	v_mfma_f32_16x16x32_bf16 v[110:113], v[130:133], v[206:209], v[110:113]
	v_mfma_f32_16x16x32_bf16 v[110:113], v[134:137], v[210:213], v[110:113]
	v_mfma_f32_16x16x32_bf16 v[102:105], v[138:141], v[206:209], v[102:105]
	v_mfma_f32_16x16x32_bf16 v[102:105], v[142:145], v[210:213], v[102:105]
	v_mfma_f32_16x16x32_bf16 v[82:85], v[168:171], v[206:209], v[82:85]
	v_mfma_f32_16x16x32_bf16 v[82:85], v[172:175], v[210:213], v[82:85]
	v_mfma_f32_16x16x32_bf16 v[78:81], v[176:179], v[206:209], v[78:81]
	v_mfma_f32_16x16x32_bf16 v[78:81], v[180:183], v[210:213], v[78:81]
	v_mfma_f32_16x16x32_bf16 v[94:97], v[130:133], v[214:217], v[94:97]
	v_mfma_f32_16x16x32_bf16 v[94:97], v[134:137], v[226:229], v[94:97]
	v_mfma_f32_16x16x32_bf16 v[74:77], v[138:141], v[214:217], v[74:77]
	v_mfma_f32_16x16x32_bf16 v[74:77], v[142:145], v[226:229], v[74:77]
	v_mfma_f32_16x16x32_bf16 v[70:73], v[168:171], v[214:217], v[70:73]
	v_mfma_f32_16x16x32_bf16 v[70:73], v[172:175], v[226:229], v[70:73]
	v_mfma_f32_16x16x32_bf16 v[66:69], v[176:179], v[214:217], v[66:69]
	v_mfma_f32_16x16x32_bf16 v[66:69], v[180:183], v[226:229], v[66:69]
	s_barrier
	s_add_i32 s52, s52, s70
	v_lshl_add_u64 v[160:161], v[160:161], 0, s[56:57]
	s_mov_b32 m0, s52
	ds_read_b128 v[186:189], v167 offset:49152
	ds_read_b128 v[190:193], v167 offset:50176
	ds_read_b128 v[194:197], v167 offset:51200
	ds_read_b128 v[202:205], v167 offset:52224
	ds_read_b128 v[206:209], v167 offset:53248
	ds_read_b128 v[210:213], v167 offset:54272
	ds_read_b128 v[214:217], v167 offset:55296
	ds_read_b128 v[226:229], v167 offset:56320
	global_load_lds_dwordx4 v[160:161], off
	s_add_i32 m0, s52, 0x2000
	s_add_u32 s62, s66, 0x158080
	v_lshl_add_u64 v[160:161], v[230:231], 0, s[56:57]
	s_addc_u32 s63, s67, 0
	s_add_i32 s52, s53, s70
	global_load_lds_dwordx4 v[160:161], off
	v_lshl_add_u64 v[160:161], s[62:63], 0, v[148:149]
	s_mov_b32 m0, s52
	s_nop 0
	global_load_lds_dwordx4 v[160:161], off
	v_lshl_add_u64 v[160:161], s[62:63], 0, v[146:147]
	s_add_i32 m0, s52, 0x2000
	s_nop 0
	global_load_lds_dwordx4 v[160:161], off
	v_lshl_add_u64 v[160:161], v[232:233], 0, s[56:57]
	s_mov_b32 m0, s85
	s_nop 0
	global_load_lds_dwordx4 v[160:161], off
	v_lshl_add_u64 v[160:161], v[234:235], 0, s[56:57]
	s_mov_b32 m0, s86
	s_nop 0
	global_load_lds_dwordx4 v[160:161], off
	s_waitcnt vmcnt(8)
	s_waitcnt lgkmcnt(0)
	s_barrier
	s_waitcnt lgkmcnt(0)
	v_mfma_f32_16x16x32_bf16 v[62:65], v[130:133], v[186:189], v[62:65]
	v_mfma_f32_16x16x32_bf16 v[62:65], v[134:137], v[190:193], v[62:65]
	v_mfma_f32_16x16x32_bf16 v[58:61], v[138:141], v[186:189], v[58:61]
	v_mfma_f32_16x16x32_bf16 v[58:61], v[142:145], v[190:193], v[58:61]
	v_mfma_f32_16x16x32_bf16 v[42:45], v[168:171], v[186:189], v[42:45]
	v_mfma_f32_16x16x32_bf16 v[42:45], v[172:175], v[190:193], v[42:45]
	v_mfma_f32_16x16x32_bf16 v[34:37], v[176:179], v[186:189], v[34:37]
	v_mfma_f32_16x16x32_bf16 v[34:37], v[180:183], v[190:193], v[34:37]
	v_mfma_f32_16x16x32_bf16 v[54:57], v[130:133], v[194:197], v[54:57]
	v_mfma_f32_16x16x32_bf16 v[54:57], v[134:137], v[202:205], v[54:57]
	v_mfma_f32_16x16x32_bf16 v[50:53], v[138:141], v[194:197], v[50:53]
	v_mfma_f32_16x16x32_bf16 v[50:53], v[142:145], v[202:205], v[50:53]
	v_mfma_f32_16x16x32_bf16 v[26:29], v[168:171], v[194:197], v[26:29]
	v_mfma_f32_16x16x32_bf16 v[26:29], v[172:175], v[202:205], v[26:29]
	v_mfma_f32_16x16x32_bf16 v[22:25], v[176:179], v[194:197], v[22:25]
	v_mfma_f32_16x16x32_bf16 v[22:25], v[180:183], v[202:205], v[22:25]
	v_mfma_f32_16x16x32_bf16 v[46:49], v[130:133], v[206:209], v[46:49]
	v_mfma_f32_16x16x32_bf16 v[46:49], v[134:137], v[210:213], v[46:49]
	v_mfma_f32_16x16x32_bf16 v[38:41], v[138:141], v[206:209], v[38:41]
	v_mfma_f32_16x16x32_bf16 v[38:41], v[142:145], v[210:213], v[38:41]
	v_mfma_f32_16x16x32_bf16 v[18:21], v[168:171], v[206:209], v[18:21]
	v_mfma_f32_16x16x32_bf16 v[18:21], v[172:175], v[210:213], v[18:21]
	v_mfma_f32_16x16x32_bf16 v[14:17], v[176:179], v[206:209], v[14:17]
	v_mfma_f32_16x16x32_bf16 v[14:17], v[180:183], v[210:213], v[14:17]
	v_mfma_f32_16x16x32_bf16 v[30:33], v[130:133], v[214:217], v[30:33]
	v_mfma_f32_16x16x32_bf16 v[30:33], v[134:137], v[226:229], v[30:33]
	v_mfma_f32_16x16x32_bf16 v[10:13], v[138:141], v[214:217], v[10:13]
	v_mfma_f32_16x16x32_bf16 v[10:13], v[142:145], v[226:229], v[10:13]
	v_mfma_f32_16x16x32_bf16 v[6:9], v[168:171], v[214:217], v[6:9]
	v_mfma_f32_16x16x32_bf16 v[6:9], v[172:175], v[226:229], v[6:9]
	v_mfma_f32_16x16x32_bf16 v[2:5], v[176:179], v[214:217], v[2:5]
	v_mfma_f32_16x16x32_bf16 v[2:5], v[180:183], v[226:229], v[2:5]
	s_barrier
	s_add_i32 s95, s95, 2
	s_add_u32 s34, s34, 0x100
	s_addc_u32 s35, s35, 0
	s_cmpk_gt_u32 s95, 0x53
	s_mov_b64 s[62:63], s[64:65]
	s_cbranch_scc0 .LBB0_335
	s_and_b64 vcc, exec, s[58:59]
	s_cbranch_vccz .LBB0_338
	s_barrier

.LBB0_531:
	ds_read_b128 v[130:133], v188
	ds_read_b128 v[134:137], v188 offset:1024
	ds_read_b128 v[138:141], v188 offset:2048
	ds_read_b128 v[142:145], v188 offset:3072
	ds_read_b128 v[146:149], v189
	ds_read_b128 v[168:171], v189 offset:1024
	ds_read_b128 v[172:175], v189 offset:2048
	ds_read_b128 v[176:179], v189 offset:3072
	s_add_u32 s10, s8, 0xfff80080
	s_addc_u32 s11, s9, -1
	s_cmp_eq_u32 s69, 28
	s_cselect_b32 s67, s34, s11
	s_cselect_b32 s66, s35, s10
	s_cselect_b32 s11, s51, s68
	s_cselect_b32 s10, s59, s61
	v_lshl_add_u64 v[196:197], s[8:9], 0, v[162:163]
	s_add_i32 m0, s55, 0xc000
	ds_read_b128 v[180:183], v190
	ds_read_b128 v[202:205], v190 offset:1024
	ds_read_b128 v[206:209], v190 offset:2048
	ds_read_b128 v[210:213], v190 offset:3072
	ds_read_b128 v[214:217], v190 offset:4096
	ds_read_b128 v[226:229], v190 offset:5120
	ds_read_b128 v[230:233], v190 offset:6144
	ds_read_b128 v[234:237], v190 offset:7168
	global_load_lds_dwordx4 v[196:197], off
	v_lshl_add_u64 v[196:197], s[8:9], 0, v[160:161]
	s_add_i32 m0, s55, 0xe000
	s_nop 0
	global_load_lds_dwordx4 v[196:197], off
	s_waitcnt vmcnt(8)
	s_waitcnt lgkmcnt(0)
	s_barrier
	s_waitcnt lgkmcnt(0)
	v_mfma_f32_16x16x32_bf16 v[126:129], v[130:133], v[180:183], v[126:129]
	v_mfma_f32_16x16x32_bf16 v[126:129], v[134:137], v[202:205], v[126:129]
	v_mfma_f32_16x16x32_bf16 v[122:125], v[138:141], v[180:183], v[122:125]
	v_mfma_f32_16x16x32_bf16 v[122:125], v[142:145], v[202:205], v[122:125]
	v_mfma_f32_16x16x32_bf16 v[118:121], v[146:149], v[180:183], v[118:121]
	v_mfma_f32_16x16x32_bf16 v[118:121], v[168:171], v[202:205], v[118:121]
	v_mfma_f32_16x16x32_bf16 v[110:113], v[172:175], v[180:183], v[110:113]
	v_mfma_f32_16x16x32_bf16 v[110:113], v[176:179], v[202:205], v[110:113]
	v_mfma_f32_16x16x32_bf16 v[114:117], v[130:133], v[206:209], v[114:117]
	v_mfma_f32_16x16x32_bf16 v[114:117], v[134:137], v[210:213], v[114:117]
	v_mfma_f32_16x16x32_bf16 v[106:109], v[138:141], v[206:209], v[106:109]
	v_mfma_f32_16x16x32_bf16 v[106:109], v[142:145], v[210:213], v[106:109]
	v_mfma_f32_16x16x32_bf16 v[102:105], v[146:149], v[206:209], v[102:105]
	v_mfma_f32_16x16x32_bf16 v[102:105], v[168:171], v[210:213], v[102:105]
	v_mfma_f32_16x16x32_bf16 v[94:97], v[172:175], v[206:209], v[94:97]
	v_mfma_f32_16x16x32_bf16 v[94:97], v[176:179], v[210:213], v[94:97]
	v_mfma_f32_16x16x32_bf16 v[98:101], v[130:133], v[214:217], v[98:101]
	v_mfma_f32_16x16x32_bf16 v[98:101], v[134:137], v[226:229], v[98:101]
	v_mfma_f32_16x16x32_bf16 v[90:93], v[138:141], v[214:217], v[90:93]
	v_mfma_f32_16x16x32_bf16 v[90:93], v[142:145], v[226:229], v[90:93]
	v_mfma_f32_16x16x32_bf16 v[86:89], v[146:149], v[214:217], v[86:89]
	v_mfma_f32_16x16x32_bf16 v[86:89], v[168:171], v[226:229], v[86:89]
	v_mfma_f32_16x16x32_bf16 v[78:81], v[172:175], v[214:217], v[78:81]
	v_mfma_f32_16x16x32_bf16 v[78:81], v[176:179], v[226:229], v[78:81]
	v_mfma_f32_16x16x32_bf16 v[82:85], v[130:133], v[230:233], v[82:85]
	v_mfma_f32_16x16x32_bf16 v[82:85], v[134:137], v[234:237], v[82:85]
	v_mfma_f32_16x16x32_bf16 v[74:77], v[138:141], v[230:233], v[74:77]
	v_mfma_f32_16x16x32_bf16 v[74:77], v[142:145], v[234:237], v[74:77]
	v_mfma_f32_16x16x32_bf16 v[70:73], v[146:149], v[230:233], v[70:73]
	v_mfma_f32_16x16x32_bf16 v[70:73], v[168:171], v[234:237], v[70:73]
	v_mfma_f32_16x16x32_bf16 v[66:69], v[172:175], v[230:233], v[66:69]
	v_mfma_f32_16x16x32_bf16 v[66:69], v[176:179], v[234:237], v[66:69]
	s_barrier
	s_add_i32 s52, s96, s81
	v_lshl_add_u64 v[196:197], s[10:11], 0, v[152:153]
	s_mov_b32 m0, s52
	ds_read_b128 v[180:183], v190 offset:16384
	ds_read_b128 v[202:205], v190 offset:17408
	ds_read_b128 v[206:209], v190 offset:18432
	ds_read_b128 v[210:213], v190 offset:19456
	ds_read_b128 v[214:217], v190 offset:20480
	ds_read_b128 v[226:229], v190 offset:21504
	ds_read_b128 v[230:233], v190 offset:22528
	ds_read_b128 v[234:237], v190 offset:23552
	global_load_lds_dwordx4 v[196:197], off
	s_add_i32 m0, s52, 0x2000
	s_add_u32 s52, s10, 0x80000
	v_lshl_add_u64 v[238:239], s[10:11], 0, v[156:157]
	s_addc_u32 s53, s11, 0
	s_add_i32 s70, s97, s81
	global_load_lds_dwordx4 v[238:239], off
	v_lshl_add_u64 v[240:241], s[52:53], 0, v[152:153]
	s_mov_b32 m0, s70
	v_lshl_add_u64 v[242:243], s[66:67], 0, v[154:155]
	global_load_lds_dwordx4 v[240:241], off
	v_lshl_add_u64 v[240:241], s[52:53], 0, v[156:157]
	s_add_i32 m0, s70, 0x2000
	s_nop 0
	global_load_lds_dwordx4 v[240:241], off
	v_lshl_add_u64 v[240:241], s[66:67], 0, v[150:151]
	s_mov_b32 m0, s55
	s_nop 0
	global_load_lds_dwordx4 v[240:241], off
	s_mov_b32 m0, s57
	s_nop 0
	global_load_lds_dwordx4 v[242:243], off
	s_waitcnt vmcnt(8)
	s_waitcnt lgkmcnt(0)
	s_barrier
	s_waitcnt lgkmcnt(0)
	v_mfma_f32_16x16x32_bf16 v[62:65], v[130:133], v[180:183], v[62:65]
	v_mfma_f32_16x16x32_bf16 v[62:65], v[134:137], v[202:205], v[62:65]
	v_mfma_f32_16x16x32_bf16 v[58:61], v[138:141], v[180:183], v[58:61]
	v_mfma_f32_16x16x32_bf16 v[58:61], v[142:145], v[202:205], v[58:61]
	v_mfma_f32_16x16x32_bf16 v[50:53], v[146:149], v[180:183], v[50:53]
	v_mfma_f32_16x16x32_bf16 v[50:53], v[168:171], v[202:205], v[50:53]
	v_mfma_f32_16x16x32_bf16 v[42:45], v[172:175], v[180:183], v[42:45]
	v_mfma_f32_16x16x32_bf16 v[42:45], v[176:179], v[202:205], v[42:45]
	v_mfma_f32_16x16x32_bf16 v[54:57], v[130:133], v[206:209], v[54:57]
	v_mfma_f32_16x16x32_bf16 v[54:57], v[134:137], v[210:213], v[54:57]
	v_mfma_f32_16x16x32_bf16 v[46:49], v[138:141], v[206:209], v[46:49]
	v_mfma_f32_16x16x32_bf16 v[46:49], v[142:145], v[210:213], v[46:49]
	v_mfma_f32_16x16x32_bf16 v[34:37], v[146:149], v[206:209], v[34:37]
	v_mfma_f32_16x16x32_bf16 v[34:37], v[168:171], v[210:213], v[34:37]
	v_mfma_f32_16x16x32_bf16 v[26:29], v[172:175], v[206:209], v[26:29]
	v_mfma_f32_16x16x32_bf16 v[26:29], v[176:179], v[210:213], v[26:29]
	v_mfma_f32_16x16x32_bf16 v[38:41], v[130:133], v[214:217], v[38:41]
	v_mfma_f32_16x16x32_bf16 v[38:41], v[134:137], v[226:229], v[38:41]
	v_mfma_f32_16x16x32_bf16 v[30:33], v[138:141], v[214:217], v[30:33]
	v_mfma_f32_16x16x32_bf16 v[30:33], v[142:145], v[226:229], v[30:33]
	v_mfma_f32_16x16x32_bf16 v[18:21], v[146:149], v[214:217], v[18:21]
	v_mfma_f32_16x16x32_bf16 v[18:21], v[168:171], v[226:229], v[18:21]
	v_mfma_f32_16x16x32_bf16 v[10:13], v[172:175], v[214:217], v[10:13]
	v_mfma_f32_16x16x32_bf16 v[10:13], v[176:179], v[226:229], v[10:13]
	v_mfma_f32_16x16x32_bf16 v[22:25], v[130:133], v[230:233], v[22:25]
	v_mfma_f32_16x16x32_bf16 v[22:25], v[134:137], v[234:237], v[22:25]
	v_mfma_f32_16x16x32_bf16 v[14:17], v[138:141], v[230:233], v[14:17]
	v_mfma_f32_16x16x32_bf16 v[14:17], v[142:145], v[234:237], v[14:17]
	v_mfma_f32_16x16x32_bf16 v[6:9], v[146:149], v[230:233], v[6:9]
	v_mfma_f32_16x16x32_bf16 v[6:9], v[168:171], v[234:237], v[6:9]
	v_mfma_f32_16x16x32_bf16 v[2:5], v[172:175], v[230:233], v[2:5]
	v_mfma_f32_16x16x32_bf16 v[2:5], v[176:179], v[234:237], v[2:5]
	s_barrier
	s_add_i32 s70, 16, 0x18000
	s_add_i32 s71, 16, 0x1c000
	v_add_u32_e32 v142, s70, v187
	v_add_u32_e32 v158, s71, v187
	ds_read_b128 v[130:133], v142
	ds_read_b128 v[134:137], v142 offset:1024
	ds_read_b128 v[138:141], v142 offset:2048
	ds_read_b128 v[142:145], v142 offset:3072
	ds_read_b128 v[146:149], v158
	ds_read_b128 v[168:171], v158 offset:1024
	ds_read_b128 v[172:175], v158 offset:2048
	ds_read_b128 v[176:179], v158 offset:3072
	s_add_u32 s52, s66, 0x80000
	s_addc_u32 s53, s67, 0
	s_mov_b32 m0, s82
	v_lshl_add_u64 v[244:245], s[52:53], 0, v[150:151]
	ds_read_b128 v[180:183], v190 offset:32768
	ds_read_b128 v[202:205], v190 offset:33792
	ds_read_b128 v[206:209], v190 offset:34816
	ds_read_b128 v[210:213], v190 offset:35840
	ds_read_b128 v[214:217], v190 offset:36864
	ds_read_b128 v[226:229], v190 offset:37888
	ds_read_b128 v[230:233], v190 offset:38912
	ds_read_b128 v[234:237], v190 offset:39936
	global_load_lds_dwordx4 v[244:245], off
	v_lshl_add_u64 v[244:245], s[52:53], 0, v[154:155]
	s_mov_b32 m0, s83
	s_nop 0
	global_load_lds_dwordx4 v[244:245], off
	s_waitcnt vmcnt(8)
	s_waitcnt lgkmcnt(0)
	s_barrier
	s_waitcnt lgkmcnt(0)
	v_mfma_f32_16x16x32_bf16 v[126:129], v[130:133], v[180:183], v[126:129]
	v_mfma_f32_16x16x32_bf16 v[126:129], v[134:137], v[202:205], v[126:129]
	v_mfma_f32_16x16x32_bf16 v[122:125], v[138:141], v[180:183], v[122:125]
	v_mfma_f32_16x16x32_bf16 v[122:125], v[142:145], v[202:205], v[122:125]
	v_mfma_f32_16x16x32_bf16 v[118:121], v[146:149], v[180:183], v[118:121]
	v_mfma_f32_16x16x32_bf16 v[118:121], v[168:171], v[202:205], v[118:121]
	v_mfma_f32_16x16x32_bf16 v[110:113], v[172:175], v[180:183], v[110:113]
	v_mfma_f32_16x16x32_bf16 v[110:113], v[176:179], v[202:205], v[110:113]
	v_mfma_f32_16x16x32_bf16 v[114:117], v[130:133], v[206:209], v[114:117]
	v_mfma_f32_16x16x32_bf16 v[114:117], v[134:137], v[210:213], v[114:117]
	v_mfma_f32_16x16x32_bf16 v[106:109], v[138:141], v[206:209], v[106:109]
	v_mfma_f32_16x16x32_bf16 v[106:109], v[142:145], v[210:213], v[106:109]
	v_mfma_f32_16x16x32_bf16 v[102:105], v[146:149], v[206:209], v[102:105]
	v_mfma_f32_16x16x32_bf16 v[102:105], v[168:171], v[210:213], v[102:105]
	v_mfma_f32_16x16x32_bf16 v[94:97], v[172:175], v[206:209], v[94:97]
	v_mfma_f32_16x16x32_bf16 v[94:97], v[176:179], v[210:213], v[94:97]
	v_mfma_f32_16x16x32_bf16 v[98:101], v[130:133], v[214:217], v[98:101]
	v_mfma_f32_16x16x32_bf16 v[98:101], v[134:137], v[226:229], v[98:101]
	v_mfma_f32_16x16x32_bf16 v[90:93], v[138:141], v[214:217], v[90:93]
	v_mfma_f32_16x16x32_bf16 v[90:93], v[142:145], v[226:229], v[90:93]
	v_mfma_f32_16x16x32_bf16 v[86:89], v[146:149], v[214:217], v[86:89]
	v_mfma_f32_16x16x32_bf16 v[86:89], v[168:171], v[226:229], v[86:89]
	v_mfma_f32_16x16x32_bf16 v[78:81], v[172:175], v[214:217], v[78:81]
	v_mfma_f32_16x16x32_bf16 v[78:81], v[176:179], v[226:229], v[78:81]
	v_mfma_f32_16x16x32_bf16 v[82:85], v[130:133], v[230:233], v[82:85]
	v_mfma_f32_16x16x32_bf16 v[82:85], v[134:137], v[234:237], v[82:85]
	v_mfma_f32_16x16x32_bf16 v[74:77], v[138:141], v[230:233], v[74:77]
	v_mfma_f32_16x16x32_bf16 v[74:77], v[142:145], v[234:237], v[74:77]
	v_mfma_f32_16x16x32_bf16 v[70:73], v[146:149], v[230:233], v[70:73]
	v_mfma_f32_16x16x32_bf16 v[70:73], v[168:171], v[234:237], v[70:73]
	v_mfma_f32_16x16x32_bf16 v[66:69], v[172:175], v[230:233], v[66:69]
	v_mfma_f32_16x16x32_bf16 v[66:69], v[176:179], v[234:237], v[66:69]
	s_barrier
	s_add_i32 s52, s70, s81
	v_lshl_add_u64 v[196:197], v[196:197], 0, s[38:39]
	s_mov_b32 m0, s52
	ds_read_b128 v[180:183], v190 offset:49152
	ds_read_b128 v[202:205], v190 offset:50176
	ds_read_b128 v[206:209], v190 offset:51200
	ds_read_b128 v[210:213], v190 offset:52224
	ds_read_b128 v[214:217], v190 offset:53248
	ds_read_b128 v[226:229], v190 offset:54272
	ds_read_b128 v[230:233], v190 offset:55296
	ds_read_b128 v[234:237], v190 offset:56320
	global_load_lds_dwordx4 v[196:197], off
	s_add_i32 m0, s52, 0x2000
	s_add_u32 s10, s10, 0x80080
	v_lshl_add_u64 v[196:197], v[238:239], 0, s[38:39]
	s_addc_u32 s11, s11, 0
	s_add_i32 s52, s71, s81
	global_load_lds_dwordx4 v[196:197], off
	v_lshl_add_u64 v[196:197], s[10:11], 0, v[152:153]
	s_mov_b32 m0, s52
	s_nop 0
	global_load_lds_dwordx4 v[196:197], off
	v_lshl_add_u64 v[196:197], s[10:11], 0, v[156:157]
	s_add_i32 m0, s52, 0x2000
	s_nop 0
	global_load_lds_dwordx4 v[196:197], off
	v_lshl_add_u64 v[196:197], v[240:241], 0, s[38:39]
	s_mov_b32 m0, s90
	s_nop 0
	global_load_lds_dwordx4 v[196:197], off
	v_lshl_add_u64 v[196:197], v[242:243], 0, s[38:39]
	s_mov_b32 m0, s91
	s_nop 0
	global_load_lds_dwordx4 v[196:197], off
	s_waitcnt vmcnt(8)
	s_waitcnt lgkmcnt(0)
	s_barrier
	s_waitcnt lgkmcnt(0)
	v_mfma_f32_16x16x32_bf16 v[62:65], v[130:133], v[180:183], v[62:65]
	v_mfma_f32_16x16x32_bf16 v[62:65], v[134:137], v[202:205], v[62:65]
	v_mfma_f32_16x16x32_bf16 v[58:61], v[138:141], v[180:183], v[58:61]
	v_mfma_f32_16x16x32_bf16 v[58:61], v[142:145], v[202:205], v[58:61]
	v_mfma_f32_16x16x32_bf16 v[50:53], v[146:149], v[180:183], v[50:53]
	v_mfma_f32_16x16x32_bf16 v[50:53], v[168:171], v[202:205], v[50:53]
	v_mfma_f32_16x16x32_bf16 v[42:45], v[172:175], v[180:183], v[42:45]
	v_mfma_f32_16x16x32_bf16 v[42:45], v[176:179], v[202:205], v[42:45]
	v_mfma_f32_16x16x32_bf16 v[54:57], v[130:133], v[206:209], v[54:57]
	v_mfma_f32_16x16x32_bf16 v[54:57], v[134:137], v[210:213], v[54:57]
	v_mfma_f32_16x16x32_bf16 v[46:49], v[138:141], v[206:209], v[46:49]
	v_mfma_f32_16x16x32_bf16 v[46:49], v[142:145], v[210:213], v[46:49]
	v_mfma_f32_16x16x32_bf16 v[34:37], v[146:149], v[206:209], v[34:37]
	v_mfma_f32_16x16x32_bf16 v[34:37], v[168:171], v[210:213], v[34:37]
	v_mfma_f32_16x16x32_bf16 v[26:29], v[172:175], v[206:209], v[26:29]
	v_mfma_f32_16x16x32_bf16 v[26:29], v[176:179], v[210:213], v[26:29]
	v_mfma_f32_16x16x32_bf16 v[38:41], v[130:133], v[214:217], v[38:41]
	v_mfma_f32_16x16x32_bf16 v[38:41], v[134:137], v[226:229], v[38:41]
	v_mfma_f32_16x16x32_bf16 v[30:33], v[138:141], v[214:217], v[30:33]
	v_mfma_f32_16x16x32_bf16 v[30:33], v[142:145], v[226:229], v[30:33]
	v_mfma_f32_16x16x32_bf16 v[18:21], v[146:149], v[214:217], v[18:21]
	v_mfma_f32_16x16x32_bf16 v[18:21], v[168:171], v[226:229], v[18:21]
	v_mfma_f32_16x16x32_bf16 v[10:13], v[172:175], v[214:217], v[10:13]
	v_mfma_f32_16x16x32_bf16 v[10:13], v[176:179], v[226:229], v[10:13]
	v_mfma_f32_16x16x32_bf16 v[22:25], v[130:133], v[230:233], v[22:25]
	v_mfma_f32_16x16x32_bf16 v[22:25], v[134:137], v[234:237], v[22:25]
	v_mfma_f32_16x16x32_bf16 v[14:17], v[138:141], v[230:233], v[14:17]
	v_mfma_f32_16x16x32_bf16 v[14:17], v[142:145], v[234:237], v[14:17]
	v_mfma_f32_16x16x32_bf16 v[6:9], v[146:149], v[230:233], v[6:9]
	v_mfma_f32_16x16x32_bf16 v[6:9], v[168:171], v[234:237], v[6:9]
	v_mfma_f32_16x16x32_bf16 v[2:5], v[172:175], v[230:233], v[2:5]
	v_mfma_f32_16x16x32_bf16 v[2:5], v[176:179], v[234:237], v[2:5]
	s_barrier
	s_add_i32 s69, s69, 2
	s_add_u32 s61, s61, 0x100
	s_addc_u32 s68, s68, 0
	s_add_u32 s8, s8, 0x100
	s_addc_u32 s9, s9, 0
	s_cmp_gt_u32 s69, 29
	s_cbranch_scc0 .LBB0_531
	v_mov_b32_e32 v132, v185
	v_mov_b32_e32 v130, v186
	s_cmp_lt_i32 s54, 12
	v_mov_b32_e32 v131, s56
	v_add_u32_e32 v196, s89, v132
	s_cselect_b64 s[8:9], -1, 0
	s_and_saveexec_b64 s[10:11], s[8:9]
	s_xor_b64 s[66:67], exec, s[10:11]
	s_cbranch_execz .LBB0_665
	v_lshlrev_b32_e64 v133, 2, s54
	v_and_or_b32 v179, v133, 12, s88
	v_add_u32_e64 v133, s56, -16
	v_lshrrev_b32_e32 v133, 4, v133
	v_cmp_lt_i32_e64 vcc, s56, 16
	v_cmp_gt_i32_e64 s[8:9], s54, 7
	s_nop 0
	v_cndmask_b32_e32 v131, v133, v131, vcc
	v_lshlrev_b32_e64 v133, 8, s56
	v_and_b32_e32 v133, 0xf00, v133
	v_cndmask_b32_e64 v140, v133, 0, vcc
	v_lshl_or_b32 v138, v131, 4, v179
	s_and_saveexec_b64 s[10:11], s[8:9]
	s_xor_b64 s[68:69], exec, s[10:11]
	s_cbranch_execz .LBB0_567
	v_lshlrev_b32_e32 v135, 14, v138
	v_lshlrev_b32_e32 v134, 3, v130
	v_lshl_add_u32 v141, v196, 6, v135
	s_and_saveexec_b64 s[8:9], vcc
	s_cbranch_execz .LBB0_536
	v_add_u32_e32 v158, v141, v134
	v_lshl_add_u64 v[130:131], v[158:159], 2, s[18:19]
	global_store_dwordx4 v[130:131], v[126:129], off
	global_store_dwordx4 v[130:131], v[122:125], off offset:16

.LBB0_1158:
	ds_read_b128 v[150:153], v227
	ds_read_b128 v[154:157], v227 offset:1024
	ds_read_b128 v[158:161], v227 offset:2048
	ds_read_b128 v[162:165], v227 offset:3072
	ds_read_b128 v[134:137], v228
	ds_read_b128 v[138:141], v228 offset:1024
	ds_read_b128 v[142:145], v228 offset:2048
	ds_read_b128 v[146:149], v228 offset:3072
	s_mov_b64 s[6:7], s[52:53]
	s_add_u32 s52, s6, 0x100
	s_addc_u32 s53, s7, 0
	s_cmp_eq_u32 s83, 28
	s_cselect_b32 s59, s27, s53
	s_cselect_b32 s58, s34, s52
	s_cselect_b32 s57, s25, s82
	s_cselect_b32 s56, s35, s39
	v_lshl_add_u64 v[4:5], s[6:7], 0, v[208:209]
	s_add_i32 m0, s61, 0xc000
	s_waitcnt lgkmcnt(0)
	ds_read_b128 v[166:169], v229
	ds_read_b128 v[170:173], v229 offset:1024
	ds_read_b128 v[174:177], v229 offset:2048
	ds_read_b128 v[178:181], v229 offset:3072
	ds_read_b128 v[182:185], v229 offset:4096
	ds_read_b128 v[186:189], v229 offset:5120
	ds_read_b128 v[190:193], v229 offset:6144
	ds_read_b128 v[194:197], v229 offset:7168
	global_load_lds_dwordx4 v[4:5], off
	v_lshl_add_u64 v[4:5], s[6:7], 0, v[206:207]
	s_add_i32 m0, s61, 0xe000
	s_nop 0
	global_load_lds_dwordx4 v[4:5], off
	s_waitcnt vmcnt(8)
	s_waitcnt lgkmcnt(0)
	s_barrier
	s_waitcnt lgkmcnt(0)
	v_mfma_f32_16x16x32_bf16 v[130:133], v[150:153], v[166:169], v[130:133]
	v_mfma_f32_16x16x32_bf16 v[130:133], v[154:157], v[170:173], v[130:133]
	v_mfma_f32_16x16x32_bf16 v[126:129], v[158:161], v[166:169], v[126:129]
	v_mfma_f32_16x16x32_bf16 v[126:129], v[162:165], v[170:173], v[126:129]
	v_mfma_f32_16x16x32_bf16 v[110:113], v[134:137], v[166:169], v[110:113]
	v_mfma_f32_16x16x32_bf16 v[110:113], v[138:141], v[170:173], v[110:113]
	v_mfma_f32_16x16x32_bf16 v[102:105], v[142:145], v[166:169], v[102:105]
	v_mfma_f32_16x16x32_bf16 v[102:105], v[146:149], v[170:173], v[102:105]
	v_mfma_f32_16x16x32_bf16 v[122:125], v[150:153], v[174:177], v[122:125]
	v_mfma_f32_16x16x32_bf16 v[122:125], v[154:157], v[178:181], v[122:125]
	v_mfma_f32_16x16x32_bf16 v[118:121], v[158:161], v[174:177], v[118:121]
	v_mfma_f32_16x16x32_bf16 v[118:121], v[162:165], v[178:181], v[118:121]
	v_mfma_f32_16x16x32_bf16 v[94:97], v[134:137], v[174:177], v[94:97]
	v_mfma_f32_16x16x32_bf16 v[94:97], v[138:141], v[178:181], v[94:97]
	v_mfma_f32_16x16x32_bf16 v[90:93], v[142:145], v[174:177], v[90:93]
	v_mfma_f32_16x16x32_bf16 v[90:93], v[146:149], v[178:181], v[90:93]
	v_mfma_f32_16x16x32_bf16 v[114:117], v[150:153], v[182:185], v[114:117]
	v_mfma_f32_16x16x32_bf16 v[114:117], v[154:157], v[186:189], v[114:117]
	v_mfma_f32_16x16x32_bf16 v[106:109], v[158:161], v[182:185], v[106:109]
	v_mfma_f32_16x16x32_bf16 v[106:109], v[162:165], v[186:189], v[106:109]
	v_mfma_f32_16x16x32_bf16 v[82:85], v[134:137], v[182:185], v[82:85]
	v_mfma_f32_16x16x32_bf16 v[82:85], v[138:141], v[186:189], v[82:85]
	v_mfma_f32_16x16x32_bf16 v[78:81], v[142:145], v[182:185], v[78:81]
	v_mfma_f32_16x16x32_bf16 v[78:81], v[146:149], v[186:189], v[78:81]
	v_mfma_f32_16x16x32_bf16 v[98:101], v[150:153], v[190:193], v[98:101]
	v_mfma_f32_16x16x32_bf16 v[98:101], v[154:157], v[194:197], v[98:101]
	v_mfma_f32_16x16x32_bf16 v[86:89], v[158:161], v[190:193], v[86:89]
	v_mfma_f32_16x16x32_bf16 v[86:89], v[162:165], v[194:197], v[86:89]
	v_mfma_f32_16x16x32_bf16 v[74:77], v[134:137], v[190:193], v[74:77]
	v_mfma_f32_16x16x32_bf16 v[74:77], v[138:141], v[194:197], v[74:77]
	v_mfma_f32_16x16x32_bf16 v[70:73], v[142:145], v[190:193], v[70:73]
	v_mfma_f32_16x16x32_bf16 v[70:73], v[146:149], v[194:197], v[70:73]
	s_barrier
	s_add_i32 s6, s77, s60
	v_lshl_add_u64 v[4:5], s[56:57], 0, v[202:203]
	s_mov_b32 m0, s6
	ds_read_b128 v[190:193], v229 offset:16384
	ds_read_b128 v[194:197], v229 offset:17408
	ds_read_b128 v[182:185], v229 offset:18432
	ds_read_b128 v[186:189], v229 offset:19456
	ds_read_b128 v[174:177], v229 offset:20480
	ds_read_b128 v[178:181], v229 offset:21504
	ds_read_b128 v[166:169], v229 offset:22528
	ds_read_b128 v[170:173], v229 offset:23552
	global_load_lds_dwordx4 v[4:5], off
	s_add_i32 m0, s6, 0x2000
	s_add_u32 s6, s56, 0x80000
	v_lshl_add_u64 v[212:213], s[56:57], 0, v[204:205]
	s_addc_u32 s7, s57, 0
	s_add_i32 s84, s78, s60
	global_load_lds_dwordx4 v[212:213], off
	v_lshl_add_u64 v[214:215], s[6:7], 0, v[202:203]
	s_mov_b32 m0, s84
	v_lshl_add_u64 v[216:217], s[58:59], 0, v[204:205]
	global_load_lds_dwordx4 v[214:215], off
	v_lshl_add_u64 v[214:215], s[6:7], 0, v[204:205]
	s_add_i32 m0, s84, 0x2000
	v_cmp_ne_u32_e64 s[6:7], 1, v230
	global_load_lds_dwordx4 v[214:215], off
	v_lshl_add_u64 v[214:215], s[58:59], 0, v[202:203]
	s_mov_b32 m0, s61
	s_andn2_b64 vcc, exec, s[54:55]
	global_load_lds_dwordx4 v[214:215], off
	s_mov_b32 m0, s62
	s_nop 0
	global_load_lds_dwordx4 v[216:217], off
	s_waitcnt vmcnt(8)
	s_waitcnt lgkmcnt(0)
	s_barrier
	s_cbranch_vccnz .LBB0_1160
	s_waitcnt lgkmcnt(0)
	v_mfma_f32_16x16x32_bf16 v[66:69], v[150:153], v[190:193], v[66:69]
	v_mfma_f32_16x16x32_bf16 v[66:69], v[154:157], v[194:197], v[66:69]
	v_mfma_f32_16x16x32_bf16 v[62:65], v[158:161], v[190:193], v[62:65]
	v_mfma_f32_16x16x32_bf16 v[62:65], v[162:165], v[194:197], v[62:65]
	v_mfma_f32_16x16x32_bf16 v[54:57], v[134:137], v[190:193], v[54:57]
	v_mfma_f32_16x16x32_bf16 v[54:57], v[138:141], v[194:197], v[54:57]
	v_mfma_f32_16x16x32_bf16 v[46:49], v[142:145], v[190:193], v[46:49]
	v_mfma_f32_16x16x32_bf16 v[46:49], v[146:149], v[194:197], v[46:49]
	v_mfma_f32_16x16x32_bf16 v[58:61], v[150:153], v[182:185], v[58:61]
	v_mfma_f32_16x16x32_bf16 v[58:61], v[154:157], v[186:189], v[58:61]
	v_mfma_f32_16x16x32_bf16 v[50:53], v[158:161], v[182:185], v[50:53]
	v_mfma_f32_16x16x32_bf16 v[50:53], v[162:165], v[186:189], v[50:53]
	v_mfma_f32_16x16x32_bf16 v[38:41], v[134:137], v[182:185], v[38:41]
	v_mfma_f32_16x16x32_bf16 v[38:41], v[138:141], v[186:189], v[38:41]
	v_mfma_f32_16x16x32_bf16 v[30:33], v[142:145], v[182:185], v[30:33]
	v_mfma_f32_16x16x32_bf16 v[30:33], v[146:149], v[186:189], v[30:33]
	v_mfma_f32_16x16x32_bf16 v[42:45], v[150:153], v[174:177], v[42:45]
	v_mfma_f32_16x16x32_bf16 v[42:45], v[154:157], v[178:181], v[42:45]
	v_mfma_f32_16x16x32_bf16 v[34:37], v[158:161], v[174:177], v[34:37]
	v_mfma_f32_16x16x32_bf16 v[34:37], v[162:165], v[178:181], v[34:37]
	v_mfma_f32_16x16x32_bf16 v[26:29], v[134:137], v[174:177], v[26:29]
	v_mfma_f32_16x16x32_bf16 v[26:29], v[138:141], v[178:181], v[26:29]
	v_mfma_f32_16x16x32_bf16 v[18:21], v[142:145], v[174:177], v[18:21]
	v_mfma_f32_16x16x32_bf16 v[18:21], v[146:149], v[178:181], v[18:21]
	v_mfma_f32_16x16x32_bf16 v[22:25], v[150:153], v[166:169], v[22:25]
	v_mfma_f32_16x16x32_bf16 v[22:25], v[154:157], v[170:173], v[22:25]
	v_mfma_f32_16x16x32_bf16 v[14:17], v[158:161], v[166:169], v[14:17]
	v_mfma_f32_16x16x32_bf16 v[14:17], v[162:165], v[170:173], v[14:17]
	v_mfma_f32_16x16x32_bf16 v[10:13], v[134:137], v[166:169], v[10:13]
	v_mfma_f32_16x16x32_bf16 v[10:13], v[138:141], v[170:173], v[10:13]
	v_mfma_f32_16x16x32_bf16 v[6:9], v[142:145], v[166:169], v[6:9]
	v_mfma_f32_16x16x32_bf16 v[6:9], v[146:149], v[170:173], v[6:9]
.LBB0_1160:
	s_barrier
	s_add_i32 s84, 16, 0x18000
	v_add_u32_e32 v2, s84, v226
	s_add_i32 s85, 16, 0x1c000
	ds_read_b128 v[150:153], v2
	ds_read_b128 v[154:157], v2 offset:1024
	ds_read_b128 v[158:161], v2 offset:2048
	ds_read_b128 v[162:165], v2 offset:3072
	v_add_u32_e32 v2, s85, v226
	ds_read_b128 v[134:137], v2
	ds_read_b128 v[138:141], v2 offset:1024
	ds_read_b128 v[142:145], v2 offset:2048
	ds_read_b128 v[146:149], v2 offset:3072
	s_add_u32 s58, s58, 0x80000
	s_addc_u32 s59, s59, 0
	s_mov_b32 m0, s63
	v_lshl_add_u64 v[232:233], s[58:59], 0, v[202:203]
	s_waitcnt lgkmcnt(0)
	ds_read_b128 v[166:169], v229 offset:32768
	ds_read_b128 v[170:173], v229 offset:33792
	ds_read_b128 v[174:177], v229 offset:34816
	ds_read_b128 v[178:181], v229 offset:35840
	ds_read_b128 v[182:185], v229 offset:36864
	ds_read_b128 v[186:189], v229 offset:37888
	ds_read_b128 v[190:193], v229 offset:38912
	ds_read_b128 v[194:197], v229 offset:39936
	global_load_lds_dwordx4 v[232:233], off
	v_lshl_add_u64 v[232:233], s[58:59], 0, v[204:205]
	s_mov_b32 m0, s64
	s_nop 0
	global_load_lds_dwordx4 v[232:233], off
	s_waitcnt vmcnt(8)
	s_waitcnt lgkmcnt(0)
	s_barrier
	s_waitcnt lgkmcnt(0)
	v_mfma_f32_16x16x32_bf16 v[130:133], v[150:153], v[166:169], v[130:133]
	v_mfma_f32_16x16x32_bf16 v[130:133], v[154:157], v[170:173], v[130:133]
	v_mfma_f32_16x16x32_bf16 v[126:129], v[158:161], v[166:169], v[126:129]
	v_mfma_f32_16x16x32_bf16 v[126:129], v[162:165], v[170:173], v[126:129]
	v_mfma_f32_16x16x32_bf16 v[110:113], v[134:137], v[166:169], v[110:113]
	v_mfma_f32_16x16x32_bf16 v[110:113], v[138:141], v[170:173], v[110:113]
	v_mfma_f32_16x16x32_bf16 v[102:105], v[142:145], v[166:169], v[102:105]
	v_mfma_f32_16x16x32_bf16 v[102:105], v[146:149], v[170:173], v[102:105]
	v_mfma_f32_16x16x32_bf16 v[122:125], v[150:153], v[174:177], v[122:125]
	v_mfma_f32_16x16x32_bf16 v[122:125], v[154:157], v[178:181], v[122:125]
	v_mfma_f32_16x16x32_bf16 v[118:121], v[158:161], v[174:177], v[118:121]
	v_mfma_f32_16x16x32_bf16 v[118:121], v[162:165], v[178:181], v[118:121]
	v_mfma_f32_16x16x32_bf16 v[94:97], v[134:137], v[174:177], v[94:97]
	v_mfma_f32_16x16x32_bf16 v[94:97], v[138:141], v[178:181], v[94:97]
	v_mfma_f32_16x16x32_bf16 v[90:93], v[142:145], v[174:177], v[90:93]
	v_mfma_f32_16x16x32_bf16 v[90:93], v[146:149], v[178:181], v[90:93]
	v_mfma_f32_16x16x32_bf16 v[114:117], v[150:153], v[182:185], v[114:117]
	v_mfma_f32_16x16x32_bf16 v[114:117], v[154:157], v[186:189], v[114:117]
	v_mfma_f32_16x16x32_bf16 v[106:109], v[158:161], v[182:185], v[106:109]
	v_mfma_f32_16x16x32_bf16 v[106:109], v[162:165], v[186:189], v[106:109]
	v_mfma_f32_16x16x32_bf16 v[82:85], v[134:137], v[182:185], v[82:85]
	v_mfma_f32_16x16x32_bf16 v[82:85], v[138:141], v[186:189], v[82:85]
	v_mfma_f32_16x16x32_bf16 v[78:81], v[142:145], v[182:185], v[78:81]
	v_mfma_f32_16x16x32_bf16 v[78:81], v[146:149], v[186:189], v[78:81]
	v_mfma_f32_16x16x32_bf16 v[98:101], v[150:153], v[190:193], v[98:101]
	v_mfma_f32_16x16x32_bf16 v[98:101], v[154:157], v[194:197], v[98:101]
	v_mfma_f32_16x16x32_bf16 v[86:89], v[158:161], v[190:193], v[86:89]
	v_mfma_f32_16x16x32_bf16 v[86:89], v[162:165], v[194:197], v[86:89]
	v_mfma_f32_16x16x32_bf16 v[74:77], v[134:137], v[190:193], v[74:77]
	v_mfma_f32_16x16x32_bf16 v[74:77], v[138:141], v[194:197], v[74:77]
	v_mfma_f32_16x16x32_bf16 v[70:73], v[142:145], v[190:193], v[70:73]
	v_mfma_f32_16x16x32_bf16 v[70:73], v[146:149], v[194:197], v[70:73]
	s_barrier
	s_add_i32 s58, s84, s60
	v_lshl_add_u64 v[4:5], v[4:5], 0, s[10:11]
	s_mov_b32 m0, s58
	ds_read_b128 v[190:193], v229 offset:49152
	ds_read_b128 v[194:197], v229 offset:50176
	ds_read_b128 v[182:185], v229 offset:51200
	ds_read_b128 v[186:189], v229 offset:52224
	ds_read_b128 v[174:177], v229 offset:53248
	ds_read_b128 v[178:181], v229 offset:54272
	ds_read_b128 v[166:169], v229 offset:55296
	ds_read_b128 v[170:173], v229 offset:56320
	global_load_lds_dwordx4 v[4:5], off
	s_add_i32 m0, s58, 0x2000
	s_add_u32 s56, s56, 0x80080
	v_lshl_add_u64 v[4:5], v[212:213], 0, s[10:11]
	s_addc_u32 s57, s57, 0
	s_add_i32 s58, s85, s60
	global_load_lds_dwordx4 v[4:5], off
	v_lshl_add_u64 v[4:5], s[56:57], 0, v[202:203]
	s_mov_b32 m0, s58
	s_and_b64 vcc, exec, s[6:7]
	global_load_lds_dwordx4 v[4:5], off
	v_lshl_add_u64 v[4:5], s[56:57], 0, v[204:205]
	s_add_i32 m0, s58, 0x2000
	s_nop 0
	global_load_lds_dwordx4 v[4:5], off
	v_lshl_add_u64 v[4:5], v[214:215], 0, s[10:11]
	s_mov_b32 m0, s70
	s_nop 0
	global_load_lds_dwordx4 v[4:5], off
	v_lshl_add_u64 v[4:5], v[216:217], 0, s[10:11]
	s_mov_b32 m0, s71
	s_nop 0
	global_load_lds_dwordx4 v[4:5], off
	s_waitcnt vmcnt(8)
	s_waitcnt lgkmcnt(0)
	s_barrier
	s_cbranch_vccnz .LBB0_1157
	s_waitcnt lgkmcnt(0)
	v_mfma_f32_16x16x32_bf16 v[66:69], v[150:153], v[190:193], v[66:69]
	v_mfma_f32_16x16x32_bf16 v[66:69], v[154:157], v[194:197], v[66:69]
	v_mfma_f32_16x16x32_bf16 v[62:65], v[158:161], v[190:193], v[62:65]
	v_mfma_f32_16x16x32_bf16 v[62:65], v[162:165], v[194:197], v[62:65]
	v_mfma_f32_16x16x32_bf16 v[54:57], v[134:137], v[190:193], v[54:57]
	v_mfma_f32_16x16x32_bf16 v[54:57], v[138:141], v[194:197], v[54:57]
	v_mfma_f32_16x16x32_bf16 v[46:49], v[142:145], v[190:193], v[46:49]
	v_mfma_f32_16x16x32_bf16 v[46:49], v[146:149], v[194:197], v[46:49]
	v_mfma_f32_16x16x32_bf16 v[58:61], v[150:153], v[182:185], v[58:61]
	v_mfma_f32_16x16x32_bf16 v[58:61], v[154:157], v[186:189], v[58:61]
	v_mfma_f32_16x16x32_bf16 v[50:53], v[158:161], v[182:185], v[50:53]
	v_mfma_f32_16x16x32_bf16 v[50:53], v[162:165], v[186:189], v[50:53]
	v_mfma_f32_16x16x32_bf16 v[38:41], v[134:137], v[182:185], v[38:41]
	v_mfma_f32_16x16x32_bf16 v[38:41], v[138:141], v[186:189], v[38:41]
	v_mfma_f32_16x16x32_bf16 v[30:33], v[142:145], v[182:185], v[30:33]
	v_mfma_f32_16x16x32_bf16 v[30:33], v[146:149], v[186:189], v[30:33]
	v_mfma_f32_16x16x32_bf16 v[42:45], v[150:153], v[174:177], v[42:45]
	v_mfma_f32_16x16x32_bf16 v[42:45], v[154:157], v[178:181], v[42:45]
	v_mfma_f32_16x16x32_bf16 v[34:37], v[158:161], v[174:177], v[34:37]
	v_mfma_f32_16x16x32_bf16 v[34:37], v[162:165], v[178:181], v[34:37]
	v_mfma_f32_16x16x32_bf16 v[26:29], v[134:137], v[174:177], v[26:29]
	v_mfma_f32_16x16x32_bf16 v[26:29], v[138:141], v[178:181], v[26:29]
	v_mfma_f32_16x16x32_bf16 v[18:21], v[142:145], v[174:177], v[18:21]
	v_mfma_f32_16x16x32_bf16 v[18:21], v[146:149], v[178:181], v[18:21]
	v_mfma_f32_16x16x32_bf16 v[22:25], v[150:153], v[166:169], v[22:25]
	v_mfma_f32_16x16x32_bf16 v[22:25], v[154:157], v[170:173], v[22:25]
	v_mfma_f32_16x16x32_bf16 v[14:17], v[158:161], v[166:169], v[14:17]
	v_mfma_f32_16x16x32_bf16 v[14:17], v[162:165], v[170:173], v[14:17]
	v_mfma_f32_16x16x32_bf16 v[10:13], v[134:137], v[166:169], v[10:13]
	v_mfma_f32_16x16x32_bf16 v[10:13], v[138:141], v[170:173], v[10:13]
	v_mfma_f32_16x16x32_bf16 v[4:7], v[142:145], v[166:169], v[6:9]
	v_mfma_f32_16x16x32_bf16 v[6:9], v[146:149], v[170:173], v[4:7]
	s_branch .LBB0_1157

.LBB0_1297:
	ds_read_b128 v[154:157], v150
	ds_read_b128 v[158:161], v150 offset:1024
	ds_read_b128 v[162:165], v150 offset:2048
	ds_read_b128 v[166:169], v150 offset:3072
	ds_read_b128 v[170:173], v151
	ds_read_b128 v[174:177], v151 offset:1024
	ds_read_b128 v[178:181], v151 offset:2048
	ds_read_b128 v[182:185], v151 offset:3072
	s_add_u32 s36, s30, 0xfff80080
	s_addc_u32 s37, s31, -1
	s_cmp_eq_u32 s66, 28
	s_cselect_b32 s39, s23, s37
	s_cselect_b32 s38, s34, s36
	s_cselect_b32 s37, s21, s65
	s_cselect_b32 s36, s35, s64
	v_lshl_add_u64 v[220:221], s[30:31], 0, v[142:143]
	s_add_i32 m0, s29, 0xc000
	ds_read_b128 v[186:189], v152
	ds_read_b128 v[190:193], v152 offset:1024
	ds_read_b128 v[194:197], v152 offset:2048
	ds_read_b128 v[198:201], v152 offset:3072
	ds_read_b128 v[202:205], v152 offset:4096
	ds_read_b128 v[206:209], v152 offset:5120
	ds_read_b128 v[210:213], v152 offset:6144
	ds_read_b128 v[214:217], v152 offset:7168
	global_load_lds_dwordx4 v[220:221], off
	v_lshl_add_u64 v[220:221], s[30:31], 0, v[140:141]
	s_add_i32 m0, s29, 0xe000
	s_nop 0
	global_load_lds_dwordx4 v[220:221], off
	s_waitcnt vmcnt(8)
	s_waitcnt lgkmcnt(0)
	s_barrier
	s_waitcnt lgkmcnt(0)
	v_mfma_f32_16x16x32_bf16 v[126:129], v[154:157], v[186:189], v[126:129]
	v_mfma_f32_16x16x32_bf16 v[126:129], v[158:161], v[190:193], v[126:129]
	v_mfma_f32_16x16x32_bf16 v[122:125], v[162:165], v[186:189], v[122:125]
	v_mfma_f32_16x16x32_bf16 v[122:125], v[166:169], v[190:193], v[122:125]
	v_mfma_f32_16x16x32_bf16 v[118:121], v[170:173], v[186:189], v[118:121]
	v_mfma_f32_16x16x32_bf16 v[118:121], v[174:177], v[190:193], v[118:121]
	v_mfma_f32_16x16x32_bf16 v[114:117], v[178:181], v[186:189], v[114:117]
	v_mfma_f32_16x16x32_bf16 v[114:117], v[182:185], v[190:193], v[114:117]
	v_mfma_f32_16x16x32_bf16 v[110:113], v[154:157], v[194:197], v[110:113]
	v_mfma_f32_16x16x32_bf16 v[110:113], v[158:161], v[198:201], v[110:113]
	v_mfma_f32_16x16x32_bf16 v[106:109], v[162:165], v[194:197], v[106:109]
	v_mfma_f32_16x16x32_bf16 v[106:109], v[166:169], v[198:201], v[106:109]
	v_mfma_f32_16x16x32_bf16 v[102:105], v[170:173], v[194:197], v[102:105]
	v_mfma_f32_16x16x32_bf16 v[102:105], v[174:177], v[198:201], v[102:105]
	v_mfma_f32_16x16x32_bf16 v[98:101], v[178:181], v[194:197], v[98:101]
	v_mfma_f32_16x16x32_bf16 v[98:101], v[182:185], v[198:201], v[98:101]
	v_mfma_f32_16x16x32_bf16 v[94:97], v[154:157], v[202:205], v[94:97]
	v_mfma_f32_16x16x32_bf16 v[94:97], v[158:161], v[206:209], v[94:97]
	v_mfma_f32_16x16x32_bf16 v[90:93], v[162:165], v[202:205], v[90:93]
	v_mfma_f32_16x16x32_bf16 v[90:93], v[166:169], v[206:209], v[90:93]
	v_mfma_f32_16x16x32_bf16 v[86:89], v[170:173], v[202:205], v[86:89]
	v_mfma_f32_16x16x32_bf16 v[86:89], v[174:177], v[206:209], v[86:89]
	v_mfma_f32_16x16x32_bf16 v[82:85], v[178:181], v[202:205], v[82:85]
	v_mfma_f32_16x16x32_bf16 v[82:85], v[182:185], v[206:209], v[82:85]
	v_mfma_f32_16x16x32_bf16 v[78:81], v[154:157], v[210:213], v[78:81]
	v_mfma_f32_16x16x32_bf16 v[78:81], v[158:161], v[214:217], v[78:81]
	v_mfma_f32_16x16x32_bf16 v[74:77], v[162:165], v[210:213], v[74:77]
	v_mfma_f32_16x16x32_bf16 v[74:77], v[166:169], v[214:217], v[74:77]
	v_mfma_f32_16x16x32_bf16 v[70:73], v[170:173], v[210:213], v[70:73]
	v_mfma_f32_16x16x32_bf16 v[70:73], v[174:177], v[214:217], v[70:73]
	v_mfma_f32_16x16x32_bf16 v[66:69], v[178:181], v[210:213], v[66:69]
	v_mfma_f32_16x16x32_bf16 v[66:69], v[182:185], v[214:217], v[66:69]
	s_barrier
	s_add_i32 s67, s60, s48
	v_lshl_add_u64 v[220:221], s[36:37], 0, v[134:135]
	s_mov_b32 m0, s67
	ds_read_b128 v[186:189], v152 offset:16384
	ds_read_b128 v[190:193], v152 offset:17408
	ds_read_b128 v[194:197], v152 offset:18432
	ds_read_b128 v[198:201], v152 offset:19456
	ds_read_b128 v[202:205], v152 offset:20480
	ds_read_b128 v[206:209], v152 offset:21504
	ds_read_b128 v[210:213], v152 offset:22528
	ds_read_b128 v[214:217], v152 offset:23552
	global_load_lds_dwordx4 v[220:221], off
	s_add_i32 m0, s67, 0x2000
	s_add_u32 s68, s36, 0x80000
	v_lshl_add_u64 v[222:223], s[36:37], 0, v[130:131]
	s_addc_u32 s69, s37, 0
	s_add_i32 s67, s61, s48
	global_load_lds_dwordx4 v[222:223], off
	v_lshl_add_u64 v[224:225], s[68:69], 0, v[134:135]
	s_mov_b32 m0, s67
	v_lshl_add_u64 v[226:227], s[38:39], 0, v[132:133]
	global_load_lds_dwordx4 v[224:225], off
	v_lshl_add_u64 v[224:225], s[68:69], 0, v[130:131]
	s_add_i32 m0, s67, 0x2000
	s_nop 0
	global_load_lds_dwordx4 v[224:225], off
	v_lshl_add_u64 v[224:225], s[38:39], 0, v[136:137]
	s_mov_b32 m0, s29
	s_nop 0
	global_load_lds_dwordx4 v[224:225], off
	s_mov_b32 m0, s51
	s_nop 0
	global_load_lds_dwordx4 v[226:227], off
	s_waitcnt vmcnt(8)
	s_waitcnt lgkmcnt(0)
	s_barrier
	s_waitcnt lgkmcnt(0)
	v_mfma_f32_16x16x32_bf16 v[62:65], v[154:157], v[186:189], v[62:65]
	v_mfma_f32_16x16x32_bf16 v[62:65], v[158:161], v[190:193], v[62:65]
	v_mfma_f32_16x16x32_bf16 v[58:61], v[162:165], v[186:189], v[58:61]
	v_mfma_f32_16x16x32_bf16 v[58:61], v[166:169], v[190:193], v[58:61]
	v_mfma_f32_16x16x32_bf16 v[54:57], v[170:173], v[186:189], v[54:57]
	v_mfma_f32_16x16x32_bf16 v[54:57], v[174:177], v[190:193], v[54:57]
	v_mfma_f32_16x16x32_bf16 v[50:53], v[178:181], v[186:189], v[50:53]
	v_mfma_f32_16x16x32_bf16 v[50:53], v[182:185], v[190:193], v[50:53]
	v_mfma_f32_16x16x32_bf16 v[46:49], v[154:157], v[194:197], v[46:49]
	v_mfma_f32_16x16x32_bf16 v[46:49], v[158:161], v[198:201], v[46:49]
	v_mfma_f32_16x16x32_bf16 v[42:45], v[162:165], v[194:197], v[42:45]
	v_mfma_f32_16x16x32_bf16 v[42:45], v[166:169], v[198:201], v[42:45]
	v_mfma_f32_16x16x32_bf16 v[38:41], v[170:173], v[194:197], v[38:41]
	v_mfma_f32_16x16x32_bf16 v[38:41], v[174:177], v[198:201], v[38:41]
	v_mfma_f32_16x16x32_bf16 v[34:37], v[178:181], v[194:197], v[34:37]
	v_mfma_f32_16x16x32_bf16 v[34:37], v[182:185], v[198:201], v[34:37]
	v_mfma_f32_16x16x32_bf16 v[30:33], v[154:157], v[202:205], v[30:33]
	v_mfma_f32_16x16x32_bf16 v[30:33], v[158:161], v[206:209], v[30:33]
	v_mfma_f32_16x16x32_bf16 v[26:29], v[162:165], v[202:205], v[26:29]
	v_mfma_f32_16x16x32_bf16 v[26:29], v[166:169], v[206:209], v[26:29]
	v_mfma_f32_16x16x32_bf16 v[22:25], v[170:173], v[202:205], v[22:25]
	v_mfma_f32_16x16x32_bf16 v[22:25], v[174:177], v[206:209], v[22:25]
	v_mfma_f32_16x16x32_bf16 v[18:21], v[178:181], v[202:205], v[18:21]
	v_mfma_f32_16x16x32_bf16 v[18:21], v[182:185], v[206:209], v[18:21]
	v_mfma_f32_16x16x32_bf16 v[14:17], v[154:157], v[210:213], v[14:17]
	v_mfma_f32_16x16x32_bf16 v[14:17], v[158:161], v[214:217], v[14:17]
	v_mfma_f32_16x16x32_bf16 v[10:13], v[162:165], v[210:213], v[10:13]
	v_mfma_f32_16x16x32_bf16 v[10:13], v[166:169], v[214:217], v[10:13]
	v_mfma_f32_16x16x32_bf16 v[6:9], v[170:173], v[210:213], v[6:9]
	v_mfma_f32_16x16x32_bf16 v[6:9], v[174:177], v[214:217], v[6:9]
	v_mfma_f32_16x16x32_bf16 v[2:5], v[178:181], v[210:213], v[2:5]
	v_mfma_f32_16x16x32_bf16 v[2:5], v[182:185], v[214:217], v[2:5]
	s_barrier
	s_add_i32 s67, 16, 0x18000
	v_add_u32_e32 v138, s67, v149
	s_add_i32 s68, 16, 0x1c000
	ds_read_b128 v[154:157], v138
	ds_read_b128 v[158:161], v138 offset:1024
	ds_read_b128 v[162:165], v138 offset:2048
	ds_read_b128 v[166:169], v138 offset:3072
	v_add_u32_e32 v138, s68, v149
	ds_read_b128 v[170:173], v138
	ds_read_b128 v[174:177], v138 offset:1024
	ds_read_b128 v[178:181], v138 offset:2048
	ds_read_b128 v[182:185], v138 offset:3072
	s_add_u32 s38, s38, 0x80000
	s_addc_u32 s39, s39, 0
	s_mov_b32 m0, s52
	v_lshl_add_u64 v[228:229], s[38:39], 0, v[136:137]
	ds_read_b128 v[186:189], v152 offset:32768
	ds_read_b128 v[190:193], v152 offset:33792
	ds_read_b128 v[194:197], v152 offset:34816
	ds_read_b128 v[198:201], v152 offset:35840
	ds_read_b128 v[202:205], v152 offset:36864
	ds_read_b128 v[206:209], v152 offset:37888
	ds_read_b128 v[210:213], v152 offset:38912
	ds_read_b128 v[214:217], v152 offset:39936
	global_load_lds_dwordx4 v[228:229], off
	v_lshl_add_u64 v[228:229], s[38:39], 0, v[132:133]
	s_mov_b32 m0, s53
	s_nop 0
	global_load_lds_dwordx4 v[228:229], off
	s_waitcnt vmcnt(8)
	s_waitcnt lgkmcnt(0)
	s_barrier
	s_waitcnt lgkmcnt(0)
	v_mfma_f32_16x16x32_bf16 v[126:129], v[154:157], v[186:189], v[126:129]
	v_mfma_f32_16x16x32_bf16 v[126:129], v[158:161], v[190:193], v[126:129]
	v_mfma_f32_16x16x32_bf16 v[122:125], v[162:165], v[186:189], v[122:125]
	v_mfma_f32_16x16x32_bf16 v[122:125], v[166:169], v[190:193], v[122:125]
	v_mfma_f32_16x16x32_bf16 v[118:121], v[170:173], v[186:189], v[118:121]
	v_mfma_f32_16x16x32_bf16 v[118:121], v[174:177], v[190:193], v[118:121]
	v_mfma_f32_16x16x32_bf16 v[114:117], v[178:181], v[186:189], v[114:117]
	v_mfma_f32_16x16x32_bf16 v[114:117], v[182:185], v[190:193], v[114:117]
	v_mfma_f32_16x16x32_bf16 v[110:113], v[154:157], v[194:197], v[110:113]
	v_mfma_f32_16x16x32_bf16 v[110:113], v[158:161], v[198:201], v[110:113]
	v_mfma_f32_16x16x32_bf16 v[106:109], v[162:165], v[194:197], v[106:109]
	v_mfma_f32_16x16x32_bf16 v[106:109], v[166:169], v[198:201], v[106:109]
	v_mfma_f32_16x16x32_bf16 v[102:105], v[170:173], v[194:197], v[102:105]
	v_mfma_f32_16x16x32_bf16 v[102:105], v[174:177], v[198:201], v[102:105]
	v_mfma_f32_16x16x32_bf16 v[98:101], v[178:181], v[194:197], v[98:101]
	v_mfma_f32_16x16x32_bf16 v[98:101], v[182:185], v[198:201], v[98:101]
	v_mfma_f32_16x16x32_bf16 v[94:97], v[154:157], v[202:205], v[94:97]
	v_mfma_f32_16x16x32_bf16 v[94:97], v[158:161], v[206:209], v[94:97]
	v_mfma_f32_16x16x32_bf16 v[90:93], v[162:165], v[202:205], v[90:93]
	v_mfma_f32_16x16x32_bf16 v[90:93], v[166:169], v[206:209], v[90:93]
	v_mfma_f32_16x16x32_bf16 v[86:89], v[170:173], v[202:205], v[86:89]
	v_mfma_f32_16x16x32_bf16 v[86:89], v[174:177], v[206:209], v[86:89]
	v_mfma_f32_16x16x32_bf16 v[82:85], v[178:181], v[202:205], v[82:85]
	v_mfma_f32_16x16x32_bf16 v[82:85], v[182:185], v[206:209], v[82:85]
	v_mfma_f32_16x16x32_bf16 v[78:81], v[154:157], v[210:213], v[78:81]
	v_mfma_f32_16x16x32_bf16 v[78:81], v[158:161], v[214:217], v[78:81]
	v_mfma_f32_16x16x32_bf16 v[74:77], v[162:165], v[210:213], v[74:77]
	v_mfma_f32_16x16x32_bf16 v[74:77], v[166:169], v[214:217], v[74:77]
	v_mfma_f32_16x16x32_bf16 v[70:73], v[170:173], v[210:213], v[70:73]
	v_mfma_f32_16x16x32_bf16 v[70:73], v[174:177], v[214:217], v[70:73]
	v_mfma_f32_16x16x32_bf16 v[66:69], v[178:181], v[210:213], v[66:69]
	v_mfma_f32_16x16x32_bf16 v[66:69], v[182:185], v[214:217], v[66:69]
	s_barrier
	s_add_i32 s38, s67, s48
	v_lshl_add_u64 v[220:221], v[220:221], 0, s[16:17]
	s_mov_b32 m0, s38
	ds_read_b128 v[186:189], v152 offset:49152
	ds_read_b128 v[190:193], v152 offset:50176
	ds_read_b128 v[194:197], v152 offset:51200
	ds_read_b128 v[198:201], v152 offset:52224
	ds_read_b128 v[202:205], v152 offset:53248
	ds_read_b128 v[206:209], v152 offset:54272
	ds_read_b128 v[210:213], v152 offset:55296
	ds_read_b128 v[214:217], v152 offset:56320
	global_load_lds_dwordx4 v[220:221], off
	s_add_i32 m0, s38, 0x2000
	s_add_u32 s36, s36, 0x80080
	v_lshl_add_u64 v[220:221], v[222:223], 0, s[16:17]
	s_addc_u32 s37, s37, 0
	s_add_i32 s38, s68, s48
	global_load_lds_dwordx4 v[220:221], off
	v_lshl_add_u64 v[220:221], s[36:37], 0, v[134:135]
	s_mov_b32 m0, s38
	s_nop 0
	global_load_lds_dwordx4 v[220:221], off
	v_lshl_add_u64 v[220:221], s[36:37], 0, v[130:131]
	s_add_i32 m0, s38, 0x2000
	s_nop 0
	global_load_lds_dwordx4 v[220:221], off
	v_lshl_add_u64 v[220:221], v[224:225], 0, s[16:17]
	s_mov_b32 m0, s57
	s_nop 0
	global_load_lds_dwordx4 v[220:221], off
	v_lshl_add_u64 v[220:221], v[226:227], 0, s[16:17]
	s_mov_b32 m0, s58
	s_nop 0
	global_load_lds_dwordx4 v[220:221], off
	s_waitcnt vmcnt(8)
	s_waitcnt lgkmcnt(0)
	s_barrier
	s_waitcnt lgkmcnt(0)
	v_mfma_f32_16x16x32_bf16 v[62:65], v[154:157], v[186:189], v[62:65]
	v_mfma_f32_16x16x32_bf16 v[62:65], v[158:161], v[190:193], v[62:65]
	v_mfma_f32_16x16x32_bf16 v[58:61], v[162:165], v[186:189], v[58:61]
	v_mfma_f32_16x16x32_bf16 v[58:61], v[166:169], v[190:193], v[58:61]
	v_mfma_f32_16x16x32_bf16 v[54:57], v[170:173], v[186:189], v[54:57]
	v_mfma_f32_16x16x32_bf16 v[54:57], v[174:177], v[190:193], v[54:57]
	v_mfma_f32_16x16x32_bf16 v[50:53], v[178:181], v[186:189], v[50:53]
	v_mfma_f32_16x16x32_bf16 v[50:53], v[182:185], v[190:193], v[50:53]
	v_mfma_f32_16x16x32_bf16 v[46:49], v[154:157], v[194:197], v[46:49]
	v_mfma_f32_16x16x32_bf16 v[46:49], v[158:161], v[198:201], v[46:49]
	v_mfma_f32_16x16x32_bf16 v[42:45], v[162:165], v[194:197], v[42:45]
	v_mfma_f32_16x16x32_bf16 v[42:45], v[166:169], v[198:201], v[42:45]
	v_mfma_f32_16x16x32_bf16 v[38:41], v[170:173], v[194:197], v[38:41]
	v_mfma_f32_16x16x32_bf16 v[38:41], v[174:177], v[198:201], v[38:41]
	v_mfma_f32_16x16x32_bf16 v[34:37], v[178:181], v[194:197], v[34:37]
	v_mfma_f32_16x16x32_bf16 v[34:37], v[182:185], v[198:201], v[34:37]
	v_mfma_f32_16x16x32_bf16 v[30:33], v[154:157], v[202:205], v[30:33]
	v_mfma_f32_16x16x32_bf16 v[30:33], v[158:161], v[206:209], v[30:33]
	v_mfma_f32_16x16x32_bf16 v[26:29], v[162:165], v[202:205], v[26:29]
	v_mfma_f32_16x16x32_bf16 v[26:29], v[166:169], v[206:209], v[26:29]
	v_mfma_f32_16x16x32_bf16 v[22:25], v[170:173], v[202:205], v[22:25]
	v_mfma_f32_16x16x32_bf16 v[22:25], v[174:177], v[206:209], v[22:25]
	v_mfma_f32_16x16x32_bf16 v[18:21], v[178:181], v[202:205], v[18:21]
	v_mfma_f32_16x16x32_bf16 v[18:21], v[182:185], v[206:209], v[18:21]
	v_mfma_f32_16x16x32_bf16 v[14:17], v[154:157], v[210:213], v[14:17]
	v_mfma_f32_16x16x32_bf16 v[14:17], v[158:161], v[214:217], v[14:17]
	v_mfma_f32_16x16x32_bf16 v[10:13], v[162:165], v[210:213], v[10:13]
	v_mfma_f32_16x16x32_bf16 v[10:13], v[166:169], v[214:217], v[10:13]
	v_mfma_f32_16x16x32_bf16 v[6:9], v[170:173], v[210:213], v[6:9]
	v_mfma_f32_16x16x32_bf16 v[6:9], v[174:177], v[214:217], v[6:9]
	v_mfma_f32_16x16x32_bf16 v[2:5], v[178:181], v[210:213], v[2:5]
	v_mfma_f32_16x16x32_bf16 v[2:5], v[182:185], v[214:217], v[2:5]
	s_barrier
	s_add_i32 s66, s66, 2
	s_add_u32 s64, s64, 0x100
	s_addc_u32 s65, s65, 0
	s_add_u32 s30, s30, 0x100
	s_addc_u32 s31, s31, 0
	s_cmp_gt_u32 s66, 29
	s_cbranch_scc0 .LBB0_1297
	s_and_b64 vcc, exec, s[18:19]
	s_cbranch_vccz .LBB0_1300
	s_barrier

.LBB0_1379:
	ds_read_b128 v[150:153], v216
	ds_read_b128 v[154:157], v216 offset:1024
	ds_read_b128 v[158:161], v216 offset:2048
	ds_read_b128 v[162:165], v216 offset:3072
	ds_read_b128 v[134:137], v217
	ds_read_b128 v[138:141], v217 offset:1024
	ds_read_b128 v[142:145], v217 offset:2048
	ds_read_b128 v[146:149], v217 offset:3072
	s_mov_b64 s[6:7], s[26:27]
	s_add_u32 s26, s6, 0x100
	s_addc_u32 s27, s7, 0
	s_cmpk_eq_i32 s69, 0x52
	s_cselect_b32 s37, s23, s27
	s_cselect_b32 s36, s22, s26
	s_cselect_b32 s31, s25, s35
	s_cselect_b32 s30, s24, s34
	v_lshl_add_u64 v[4:5], s[6:7], 0, v[204:205]
	s_add_i32 m0, s48, 0xc000
	s_waitcnt lgkmcnt(0)
	ds_read_b128 v[166:169], v219
	ds_read_b128 v[170:173], v219 offset:1024
	ds_read_b128 v[174:177], v219 offset:2048
	ds_read_b128 v[178:181], v219 offset:3072
	ds_read_b128 v[182:185], v219 offset:4096
	ds_read_b128 v[186:189], v219 offset:5120
	ds_read_b128 v[190:193], v219 offset:6144
	ds_read_b128 v[194:197], v219 offset:7168
	global_load_lds_dwordx4 v[4:5], off
	v_lshl_add_u64 v[4:5], s[6:7], 0, v[202:203]
	s_add_i32 m0, s48, 0xe000
	s_nop 0
	global_load_lds_dwordx4 v[4:5], off
	s_waitcnt vmcnt(8)
	s_waitcnt lgkmcnt(0)
	s_barrier
	s_waitcnt lgkmcnt(0)
	v_mfma_f32_16x16x32_bf16 v[130:133], v[150:153], v[166:169], v[130:133]
	v_mfma_f32_16x16x32_bf16 v[130:133], v[154:157], v[170:173], v[130:133]
	v_mfma_f32_16x16x32_bf16 v[126:129], v[158:161], v[166:169], v[126:129]
	v_mfma_f32_16x16x32_bf16 v[126:129], v[162:165], v[170:173], v[126:129]
	v_mfma_f32_16x16x32_bf16 v[110:113], v[134:137], v[166:169], v[110:113]
	v_mfma_f32_16x16x32_bf16 v[110:113], v[138:141], v[170:173], v[110:113]
	v_mfma_f32_16x16x32_bf16 v[102:105], v[142:145], v[166:169], v[102:105]
	v_mfma_f32_16x16x32_bf16 v[102:105], v[146:149], v[170:173], v[102:105]
	v_mfma_f32_16x16x32_bf16 v[122:125], v[150:153], v[174:177], v[122:125]
	v_mfma_f32_16x16x32_bf16 v[122:125], v[154:157], v[178:181], v[122:125]
	v_mfma_f32_16x16x32_bf16 v[118:121], v[158:161], v[174:177], v[118:121]
	v_mfma_f32_16x16x32_bf16 v[118:121], v[162:165], v[178:181], v[118:121]
	v_mfma_f32_16x16x32_bf16 v[94:97], v[134:137], v[174:177], v[94:97]
	v_mfma_f32_16x16x32_bf16 v[94:97], v[138:141], v[178:181], v[94:97]
	v_mfma_f32_16x16x32_bf16 v[90:93], v[142:145], v[174:177], v[90:93]
	v_mfma_f32_16x16x32_bf16 v[90:93], v[146:149], v[178:181], v[90:93]
	v_mfma_f32_16x16x32_bf16 v[114:117], v[150:153], v[182:185], v[114:117]
	v_mfma_f32_16x16x32_bf16 v[114:117], v[154:157], v[186:189], v[114:117]
	v_mfma_f32_16x16x32_bf16 v[106:109], v[158:161], v[182:185], v[106:109]
	v_mfma_f32_16x16x32_bf16 v[106:109], v[162:165], v[186:189], v[106:109]
	v_mfma_f32_16x16x32_bf16 v[82:85], v[134:137], v[182:185], v[82:85]
	v_mfma_f32_16x16x32_bf16 v[82:85], v[138:141], v[186:189], v[82:85]
	v_mfma_f32_16x16x32_bf16 v[78:81], v[142:145], v[182:185], v[78:81]
	v_mfma_f32_16x16x32_bf16 v[78:81], v[146:149], v[186:189], v[78:81]
	v_mfma_f32_16x16x32_bf16 v[98:101], v[150:153], v[190:193], v[98:101]
	v_mfma_f32_16x16x32_bf16 v[98:101], v[154:157], v[194:197], v[98:101]
	v_mfma_f32_16x16x32_bf16 v[86:89], v[158:161], v[190:193], v[86:89]
	v_mfma_f32_16x16x32_bf16 v[86:89], v[162:165], v[194:197], v[86:89]
	v_mfma_f32_16x16x32_bf16 v[74:77], v[134:137], v[190:193], v[74:77]
	v_mfma_f32_16x16x32_bf16 v[74:77], v[138:141], v[194:197], v[74:77]
	v_mfma_f32_16x16x32_bf16 v[70:73], v[142:145], v[190:193], v[70:73]
	v_mfma_f32_16x16x32_bf16 v[70:73], v[146:149], v[194:197], v[70:73]
	s_barrier
	s_add_i32 s6, s13, s47
	v_lshl_add_u64 v[4:5], s[30:31], 0, v[198:199]
	s_mov_b32 m0, s6
	ds_read_b128 v[190:193], v219 offset:16384
	ds_read_b128 v[194:197], v219 offset:17408
	ds_read_b128 v[182:185], v219 offset:18432
	ds_read_b128 v[186:189], v219 offset:19456
	ds_read_b128 v[174:177], v219 offset:20480
	ds_read_b128 v[178:181], v219 offset:21504
	ds_read_b128 v[166:169], v219 offset:22528
	ds_read_b128 v[170:173], v219 offset:23552
	global_load_lds_dwordx4 v[4:5], off
	s_add_i32 m0, s6, 0x2000
	s_add_u32 s6, s30, 0x158000
	v_lshl_add_u64 v[208:209], s[30:31], 0, v[200:201]
	s_addc_u32 s7, s31, 0
	s_add_i32 s70, s62, s47
	global_load_lds_dwordx4 v[208:209], off
	v_lshl_add_u64 v[210:211], s[6:7], 0, v[198:199]
	s_mov_b32 m0, s70
	v_lshl_add_u64 v[212:213], s[36:37], 0, v[200:201]
	global_load_lds_dwordx4 v[210:211], off
	v_lshl_add_u64 v[210:211], s[6:7], 0, v[200:201]
	s_add_i32 m0, s70, 0x2000
	v_cmp_ne_u32_e64 s[6:7], 1, v220
	global_load_lds_dwordx4 v[210:211], off
	v_lshl_add_u64 v[210:211], s[36:37], 0, v[198:199]
	s_mov_b32 m0, s48
	s_andn2_b64 vcc, exec, s[28:29]
	global_load_lds_dwordx4 v[210:211], off
	s_mov_b32 m0, s49
	s_nop 0
	global_load_lds_dwordx4 v[212:213], off
	s_waitcnt vmcnt(8)
	s_waitcnt lgkmcnt(0)
	s_barrier
	s_cbranch_vccnz .LBB0_1381
	s_waitcnt lgkmcnt(0)
	v_mfma_f32_16x16x32_bf16 v[66:69], v[150:153], v[190:193], v[66:69]
	v_mfma_f32_16x16x32_bf16 v[66:69], v[154:157], v[194:197], v[66:69]
	v_mfma_f32_16x16x32_bf16 v[62:65], v[158:161], v[190:193], v[62:65]
	v_mfma_f32_16x16x32_bf16 v[62:65], v[162:165], v[194:197], v[62:65]
	v_mfma_f32_16x16x32_bf16 v[54:57], v[134:137], v[190:193], v[54:57]
	v_mfma_f32_16x16x32_bf16 v[54:57], v[138:141], v[194:197], v[54:57]
	v_mfma_f32_16x16x32_bf16 v[46:49], v[142:145], v[190:193], v[46:49]
	v_mfma_f32_16x16x32_bf16 v[46:49], v[146:149], v[194:197], v[46:49]
	v_mfma_f32_16x16x32_bf16 v[58:61], v[150:153], v[182:185], v[58:61]
	v_mfma_f32_16x16x32_bf16 v[58:61], v[154:157], v[186:189], v[58:61]
	v_mfma_f32_16x16x32_bf16 v[50:53], v[158:161], v[182:185], v[50:53]
	v_mfma_f32_16x16x32_bf16 v[50:53], v[162:165], v[186:189], v[50:53]
	v_mfma_f32_16x16x32_bf16 v[38:41], v[134:137], v[182:185], v[38:41]
	v_mfma_f32_16x16x32_bf16 v[38:41], v[138:141], v[186:189], v[38:41]
	v_mfma_f32_16x16x32_bf16 v[30:33], v[142:145], v[182:185], v[30:33]
	v_mfma_f32_16x16x32_bf16 v[30:33], v[146:149], v[186:189], v[30:33]
	v_mfma_f32_16x16x32_bf16 v[42:45], v[150:153], v[174:177], v[42:45]
	v_mfma_f32_16x16x32_bf16 v[42:45], v[154:157], v[178:181], v[42:45]
	v_mfma_f32_16x16x32_bf16 v[34:37], v[158:161], v[174:177], v[34:37]
	v_mfma_f32_16x16x32_bf16 v[34:37], v[162:165], v[178:181], v[34:37]
	v_mfma_f32_16x16x32_bf16 v[26:29], v[134:137], v[174:177], v[26:29]
	v_mfma_f32_16x16x32_bf16 v[26:29], v[138:141], v[178:181], v[26:29]
	v_mfma_f32_16x16x32_bf16 v[18:21], v[142:145], v[174:177], v[18:21]
	v_mfma_f32_16x16x32_bf16 v[18:21], v[146:149], v[178:181], v[18:21]
	v_mfma_f32_16x16x32_bf16 v[22:25], v[150:153], v[166:169], v[22:25]
	v_mfma_f32_16x16x32_bf16 v[22:25], v[154:157], v[170:173], v[22:25]
	v_mfma_f32_16x16x32_bf16 v[14:17], v[158:161], v[166:169], v[14:17]
	v_mfma_f32_16x16x32_bf16 v[14:17], v[162:165], v[170:173], v[14:17]
	v_mfma_f32_16x16x32_bf16 v[10:13], v[134:137], v[166:169], v[10:13]
	v_mfma_f32_16x16x32_bf16 v[10:13], v[138:141], v[170:173], v[10:13]
	v_mfma_f32_16x16x32_bf16 v[6:9], v[142:145], v[166:169], v[6:9]
	v_mfma_f32_16x16x32_bf16 v[6:9], v[146:149], v[170:173], v[6:9]
.LBB0_1381:
	s_barrier
	s_add_i32 s70, 16, 0x18000
	v_add_u32_e32 v2, s70, v215
	s_add_i32 s71, 16, 0x1c000
	ds_read_b128 v[150:153], v2
	ds_read_b128 v[154:157], v2 offset:1024
	ds_read_b128 v[158:161], v2 offset:2048
	ds_read_b128 v[162:165], v2 offset:3072
	v_add_u32_e32 v2, s71, v215
	ds_read_b128 v[134:137], v2
	ds_read_b128 v[138:141], v2 offset:1024
	ds_read_b128 v[142:145], v2 offset:2048
	ds_read_b128 v[146:149], v2 offset:3072
	s_add_u32 s36, s36, 0x158000
	s_addc_u32 s37, s37, 0
	s_mov_b32 m0, s50
	v_lshl_add_u64 v[222:223], s[36:37], 0, v[198:199]
	s_waitcnt lgkmcnt(0)
	ds_read_b128 v[166:169], v219 offset:32768
	ds_read_b128 v[170:173], v219 offset:33792
	ds_read_b128 v[174:177], v219 offset:34816
	ds_read_b128 v[178:181], v219 offset:35840
	ds_read_b128 v[182:185], v219 offset:36864
	ds_read_b128 v[186:189], v219 offset:37888
	ds_read_b128 v[190:193], v219 offset:38912
	ds_read_b128 v[194:197], v219 offset:39936
	global_load_lds_dwordx4 v[222:223], off
	v_lshl_add_u64 v[222:223], s[36:37], 0, v[200:201]
	s_mov_b32 m0, s51
	s_nop 0
	global_load_lds_dwordx4 v[222:223], off
	s_waitcnt vmcnt(8)
	s_waitcnt lgkmcnt(0)
	s_barrier
	s_waitcnt lgkmcnt(0)
	v_mfma_f32_16x16x32_bf16 v[130:133], v[150:153], v[166:169], v[130:133]
	v_mfma_f32_16x16x32_bf16 v[130:133], v[154:157], v[170:173], v[130:133]
	v_mfma_f32_16x16x32_bf16 v[126:129], v[158:161], v[166:169], v[126:129]
	v_mfma_f32_16x16x32_bf16 v[126:129], v[162:165], v[170:173], v[126:129]
	v_mfma_f32_16x16x32_bf16 v[110:113], v[134:137], v[166:169], v[110:113]
	v_mfma_f32_16x16x32_bf16 v[110:113], v[138:141], v[170:173], v[110:113]
	v_mfma_f32_16x16x32_bf16 v[102:105], v[142:145], v[166:169], v[102:105]
	v_mfma_f32_16x16x32_bf16 v[102:105], v[146:149], v[170:173], v[102:105]
	v_mfma_f32_16x16x32_bf16 v[122:125], v[150:153], v[174:177], v[122:125]
	v_mfma_f32_16x16x32_bf16 v[122:125], v[154:157], v[178:181], v[122:125]
	v_mfma_f32_16x16x32_bf16 v[118:121], v[158:161], v[174:177], v[118:121]
	v_mfma_f32_16x16x32_bf16 v[118:121], v[162:165], v[178:181], v[118:121]
	v_mfma_f32_16x16x32_bf16 v[94:97], v[134:137], v[174:177], v[94:97]
	v_mfma_f32_16x16x32_bf16 v[94:97], v[138:141], v[178:181], v[94:97]
	v_mfma_f32_16x16x32_bf16 v[90:93], v[142:145], v[174:177], v[90:93]
	v_mfma_f32_16x16x32_bf16 v[90:93], v[146:149], v[178:181], v[90:93]
	v_mfma_f32_16x16x32_bf16 v[114:117], v[150:153], v[182:185], v[114:117]
	v_mfma_f32_16x16x32_bf16 v[114:117], v[154:157], v[186:189], v[114:117]
	v_mfma_f32_16x16x32_bf16 v[106:109], v[158:161], v[182:185], v[106:109]
	v_mfma_f32_16x16x32_bf16 v[106:109], v[162:165], v[186:189], v[106:109]
	v_mfma_f32_16x16x32_bf16 v[82:85], v[134:137], v[182:185], v[82:85]
	v_mfma_f32_16x16x32_bf16 v[82:85], v[138:141], v[186:189], v[82:85]
	v_mfma_f32_16x16x32_bf16 v[78:81], v[142:145], v[182:185], v[78:81]
	v_mfma_f32_16x16x32_bf16 v[78:81], v[146:149], v[186:189], v[78:81]
	v_mfma_f32_16x16x32_bf16 v[98:101], v[150:153], v[190:193], v[98:101]
	v_mfma_f32_16x16x32_bf16 v[98:101], v[154:157], v[194:197], v[98:101]
	v_mfma_f32_16x16x32_bf16 v[86:89], v[158:161], v[190:193], v[86:89]
	v_mfma_f32_16x16x32_bf16 v[86:89], v[162:165], v[194:197], v[86:89]
	v_mfma_f32_16x16x32_bf16 v[74:77], v[134:137], v[190:193], v[74:77]
	v_mfma_f32_16x16x32_bf16 v[74:77], v[138:141], v[194:197], v[74:77]
	v_mfma_f32_16x16x32_bf16 v[70:73], v[142:145], v[190:193], v[70:73]
	v_mfma_f32_16x16x32_bf16 v[70:73], v[146:149], v[194:197], v[70:73]
	s_barrier
	s_add_i32 s36, s70, s47
	v_lshl_add_u64 v[4:5], v[4:5], 0, s[10:11]
	s_mov_b32 m0, s36
	ds_read_b128 v[190:193], v219 offset:49152
	ds_read_b128 v[194:197], v219 offset:50176
	ds_read_b128 v[182:185], v219 offset:51200
	ds_read_b128 v[186:189], v219 offset:52224
	ds_read_b128 v[174:177], v219 offset:53248
	ds_read_b128 v[178:181], v219 offset:54272
	ds_read_b128 v[166:169], v219 offset:55296
	ds_read_b128 v[170:173], v219 offset:56320
	global_load_lds_dwordx4 v[4:5], off
	s_add_i32 m0, s36, 0x2000
	s_add_u32 s30, s30, 0x158080
	v_lshl_add_u64 v[4:5], v[208:209], 0, s[10:11]
	s_addc_u32 s31, s31, 0
	s_add_i32 s36, s71, s47
	global_load_lds_dwordx4 v[4:5], off
	v_lshl_add_u64 v[4:5], s[30:31], 0, v[198:199]
	s_mov_b32 m0, s36
	s_and_b64 vcc, exec, s[6:7]
	global_load_lds_dwordx4 v[4:5], off
	v_lshl_add_u64 v[4:5], s[30:31], 0, v[200:201]
	s_add_i32 m0, s36, 0x2000
	s_nop 0
	global_load_lds_dwordx4 v[4:5], off
	v_lshl_add_u64 v[4:5], v[210:211], 0, s[10:11]
	s_mov_b32 m0, s57
	s_nop 0
	global_load_lds_dwordx4 v[4:5], off
	v_lshl_add_u64 v[4:5], v[212:213], 0, s[10:11]
	s_mov_b32 m0, s58
	s_nop 0
	global_load_lds_dwordx4 v[4:5], off
	s_waitcnt vmcnt(8)
	s_waitcnt lgkmcnt(0)
	s_barrier
	s_cbranch_vccnz .LBB0_1378
	s_waitcnt lgkmcnt(0)
	v_mfma_f32_16x16x32_bf16 v[66:69], v[150:153], v[190:193], v[66:69]
	v_mfma_f32_16x16x32_bf16 v[66:69], v[154:157], v[194:197], v[66:69]
	v_mfma_f32_16x16x32_bf16 v[62:65], v[158:161], v[190:193], v[62:65]
	v_mfma_f32_16x16x32_bf16 v[62:65], v[162:165], v[194:197], v[62:65]
	v_mfma_f32_16x16x32_bf16 v[54:57], v[134:137], v[190:193], v[54:57]
	v_mfma_f32_16x16x32_bf16 v[54:57], v[138:141], v[194:197], v[54:57]
	v_mfma_f32_16x16x32_bf16 v[46:49], v[142:145], v[190:193], v[46:49]
	v_mfma_f32_16x16x32_bf16 v[46:49], v[146:149], v[194:197], v[46:49]
	v_mfma_f32_16x16x32_bf16 v[58:61], v[150:153], v[182:185], v[58:61]
	v_mfma_f32_16x16x32_bf16 v[58:61], v[154:157], v[186:189], v[58:61]
	v_mfma_f32_16x16x32_bf16 v[50:53], v[158:161], v[182:185], v[50:53]
	v_mfma_f32_16x16x32_bf16 v[50:53], v[162:165], v[186:189], v[50:53]
	v_mfma_f32_16x16x32_bf16 v[38:41], v[134:137], v[182:185], v[38:41]
	v_mfma_f32_16x16x32_bf16 v[38:41], v[138:141], v[186:189], v[38:41]
	v_mfma_f32_16x16x32_bf16 v[30:33], v[142:145], v[182:185], v[30:33]
	v_mfma_f32_16x16x32_bf16 v[30:33], v[146:149], v[186:189], v[30:33]
	v_mfma_f32_16x16x32_bf16 v[42:45], v[150:153], v[174:177], v[42:45]
	v_mfma_f32_16x16x32_bf16 v[42:45], v[154:157], v[178:181], v[42:45]
	v_mfma_f32_16x16x32_bf16 v[34:37], v[158:161], v[174:177], v[34:37]
	v_mfma_f32_16x16x32_bf16 v[34:37], v[162:165], v[178:181], v[34:37]
	v_mfma_f32_16x16x32_bf16 v[26:29], v[134:137], v[174:177], v[26:29]
	v_mfma_f32_16x16x32_bf16 v[26:29], v[138:141], v[178:181], v[26:29]
	v_mfma_f32_16x16x32_bf16 v[18:21], v[142:145], v[174:177], v[18:21]
	v_mfma_f32_16x16x32_bf16 v[18:21], v[146:149], v[178:181], v[18:21]
	v_mfma_f32_16x16x32_bf16 v[22:25], v[150:153], v[166:169], v[22:25]
	v_mfma_f32_16x16x32_bf16 v[22:25], v[154:157], v[170:173], v[22:25]
	v_mfma_f32_16x16x32_bf16 v[14:17], v[158:161], v[166:169], v[14:17]
	v_mfma_f32_16x16x32_bf16 v[14:17], v[162:165], v[170:173], v[14:17]
	v_mfma_f32_16x16x32_bf16 v[10:13], v[134:137], v[166:169], v[10:13]
	v_mfma_f32_16x16x32_bf16 v[10:13], v[138:141], v[170:173], v[10:13]
	v_mfma_f32_16x16x32_bf16 v[4:7], v[142:145], v[166:169], v[6:9]
	v_mfma_f32_16x16x32_bf16 v[6:9], v[146:149], v[170:173], v[4:7]
	s_branch .LBB0_1378
